# v26 + GEMM epilogues not aligned between the two wave halves in 8 phases (leading half skips the pre-epilogue barrier except after the last unit; trailing half skips the offset-restoring barrier)
# baseline (speedup 1.0000x reference)
; __device__ __forceinline__ unsigned cvt_pk_bf16(float lo, float hi) { const bf16x2_cv v = __builtin_convertvector((f32x2_cv){lo, hi}, bf16x2_cv); return __builtin_bit_cast(unsigned, v); }
; #define PG8_BAR __builtin_amdgcn_s_barrier()
;     __device__ __forceinline__ void operator()(const f32x4 (&acc)[2][2][4][2], const Unit& u, int wr, int wc, int fr, int fq) const {
;         const int row0 = u.pm * BM + wr * 64 + fr; const int col0 = u.pn * BM + wc * 32 + 8 * fq;
;         f32x4 bv[2][2];
;         if (BIAS) {
; #pragma unroll
;             for (int bj = 0; bj < 2; ++bj)
; #pragma unroll
;                 for (int n = 0; n < 2; ++n) bv[bj][n] = *(const f32x4*)(bias + col0 + bj * HALF + 4 * n); }
; #pragma unroll
;         for (int ai = 0; ai < 2; ++ai)
; #pragma unroll
;             for (int m = 0; m < 4; ++m) { bf16_t* rowp = O + (size_t)(row0 + ai * HALF + m * 16) * ldc + col0;
; #pragma unroll
;                 for (int bj = 0; bj < 2; ++bj) { f32x4 v0 = acc[ai][bj][m][0], v1 = acc[ai][bj][m][1]; if (BIAS) { v0 = v0 + bv[bj][0]; v1 = v1 + bv[bj][1]; }
;                     u32x4 w; w.x = cvt_pk_bf16(v0[0], v0[1]); w.y = cvt_pk_bf16(v0[2], v0[3]); w.z = cvt_pk_bf16(v1[0], v1[1]); w.w = cvt_pk_bf16(v1[2], v1[3]);
;                     *(u32x4*)(rowp + bj * HALF) = w; } }
; template <class Epi, class Sched, bool ALIGN_EPI = false, bool SP2 = false>
; __device__ __forceinline__ void gemm_phase(PG8_LAS unsigned char* lds, const Gemm g, const Sched& S, const Epi& E) {
;     ...
;         if constexpr (ALIGN_EPI) { if (wr == 0) PG8_BAR; }
;         if constexpr (!Epi::AFTER_DRAIN) { E(acc, cur, wr, wc, fr, fq); S.done(cur); }
;         if (!has_next) break;
; #pragma unroll
;         for (int a = 0; a < 2; ++a)
; #pragma unroll
;             for (int b = 0; b < 2; ++b)
; #pragma unroll
;                 for (int m = 0; m < 4; ++m)
; #pragma unroll
;                     for (int n = 0; n < 2; ++n) acc[a][b][m][n] = (f32x4){0.f, 0.f, 0.f, 0.f};
;         cur = nxt; cA = nA; cB = nB; ++ui;
;         if constexpr (ALIGN_EPI) { if (wr == 1) PG8_BAR; }
.Lpeel_exit_6:
	s_and_b64 vcc, exec, s[12:13]
	s_cbranch_vccz .LBB0_805
	s_and_b64 vcc, exec, s[4:5]
	s_cbranch_vccnz .LBB0_805
	s_barrier
.LBB0_805:
	v_lshl_add_u32 v152, s26, 8, v1
	v_lshl_or_b32 v154, s60, 8, v147
	v_ashrrev_i32_e32 v153, 31, v152
	v_readlane_b32 s38, v254, 4
	v_ashrrev_i32_e32 v155, 31, v154
	v_lshlrev_b64 v[156:157], 12, v[152:153]
	v_readlane_b32 s39, v254, 5
	v_lshlrev_b64 v[154:155], 1, v[154:155]
	v_cvt_pk_bf16_f32 v62, v62, v63
	v_lshl_add_u64 v[156:157], s[38:39], 0, v[156:157]
	v_lshl_add_u64 v[156:157], v[156:157], 0, v[154:155]
	v_cvt_pk_bf16_f32 v63, v64, v65
	v_cvt_pk_bf16_f32 v64, v58, v59
	v_add_co_u32_e32 v58, vcc, s56, v156
	v_cvt_pk_bf16_f32 v70, v70, v71
	v_cvt_pk_bf16_f32 v71, v72, v73
	v_cvt_pk_bf16_f32 v72, v66, v67
	v_lshl_add_u64 v[66:67], v[156:157], 0, s[2:3]
	v_addc_co_u32_e32 v59, vcc, 0, v157, vcc
	v_cvt_pk_bf16_f32 v46, v46, v47
	v_cvt_pk_bf16_f32 v47, v48, v49
	v_cvt_pk_bf16_f32 v48, v42, v43
	v_cvt_pk_bf16_f32 v49, v44, v45
	v_cvt_pk_bf16_f32 v110, v110, v111
	v_cvt_pk_bf16_f32 v111, v112, v113
	v_cvt_pk_bf16_f32 v112, v106, v107
	v_or_b32_e32 v106, 16, v152
	global_store_dwordx4 v[66:67], v[46:49], off offset:256
	v_ashrrev_i32_e32 v107, 31, v106
	v_cvt_pk_bf16_f32 v94, v94, v95
	v_add_co_u32_e32 v48, vcc, s57, v156
	v_cvt_pk_bf16_f32 v95, v96, v97
	v_cvt_pk_bf16_f32 v96, v90, v91
	v_or_b32_e32 v90, 32, v152
	v_lshl_add_u64 v[46:47], v[156:157], 0, s[14:15]
	v_addc_co_u32_e32 v49, vcc, 0, v157, vcc
	v_cvt_pk_bf16_f32 v30, v30, v31
	v_cvt_pk_bf16_f32 v31, v32, v33
	v_cvt_pk_bf16_f32 v32, v26, v27
	v_cvt_pk_bf16_f32 v33, v28, v29
	v_lshlrev_b64 v[106:107], 12, v[106:107]
	v_ashrrev_i32_e32 v91, 31, v90
	v_cvt_pk_bf16_f32 v78, v78, v79
	v_cvt_pk_bf16_f32 v79, v80, v81
	v_cvt_pk_bf16_f32 v80, v74, v75
	v_or_b32_e32 v74, 48, v152
	global_store_dwordx4 v[46:47], v[30:33], off offset:256
	v_cvt_pk_bf16_f32 v113, v108, v109
	v_lshl_add_u64 v[106:107], s[38:39], 0, v[106:107]
	v_add_co_u32_e32 v32, vcc, s58, v156
	v_lshlrev_b64 v[90:91], 12, v[90:91]
	v_ashrrev_i32_e32 v75, 31, v74
	v_lshl_add_u64 v[30:31], v[156:157], 0, s[16:17]
	v_addc_co_u32_e32 v33, vcc, 0, v157, vcc
	v_cvt_pk_bf16_f32 v14, v14, v15
	v_cvt_pk_bf16_f32 v15, v16, v17
	v_cvt_pk_bf16_f32 v16, v10, v11
	v_cvt_pk_bf16_f32 v17, v12, v13
	global_store_dwordx4 v[156:157], v[110:113], off offset:256
	v_cvt_pk_bf16_f32 v97, v92, v93
	v_lshl_add_u64 v[90:91], s[38:39], 0, v[90:91]
	v_lshl_add_u64 v[110:111], v[106:107], 0, v[154:155]
	v_lshlrev_b64 v[74:75], 12, v[74:75]
	global_store_dwordx4 v[30:31], v[14:17], off offset:256
	global_store_dwordx4 v[110:111], v[94:97], off offset:256
	v_cvt_pk_bf16_f32 v81, v76, v77
	v_add_co_u32_e32 v16, vcc, s59, v156
	v_lshl_add_u64 v[94:95], v[90:91], 0, v[154:155]
	v_lshl_add_u64 v[74:75], s[38:39], 0, v[74:75]
	v_addc_co_u32_e32 v17, vcc, 0, v157, vcc
	v_cvt_pk_bf16_f32 v126, v126, v127
	v_cvt_pk_bf16_f32 v127, v128, v129
	v_cvt_pk_bf16_f32 v128, v122, v123
	v_cvt_pk_bf16_f32 v129, v124, v125
	v_cvt_pk_bf16_f32 v106, v118, v119
	v_cvt_pk_bf16_f32 v107, v120, v121
	v_cvt_pk_bf16_f32 v108, v114, v115
	v_cvt_pk_bf16_f32 v109, v116, v117
	v_cvt_pk_bf16_f32 v90, v102, v103
	v_cvt_pk_bf16_f32 v91, v104, v105
	v_cvt_pk_bf16_f32 v92, v98, v99
	v_cvt_pk_bf16_f32 v93, v100, v101
	global_store_dwordx4 v[94:95], v[78:81], off offset:256
	v_cvt_pk_bf16_f32 v76, v82, v83
	v_cvt_pk_bf16_f32 v77, v84, v85
	v_lshl_add_u64 v[78:79], v[74:75], 0, v[154:155]
	v_cvt_pk_bf16_f32 v74, v86, v87
	v_cvt_pk_bf16_f32 v75, v88, v89
	v_cvt_pk_bf16_f32 v73, v68, v69
	v_cvt_pk_bf16_f32 v65, v60, v61
	v_cvt_pk_bf16_f32 v42, v54, v55
	v_cvt_pk_bf16_f32 v43, v56, v57
	v_cvt_pk_bf16_f32 v44, v50, v51
	v_cvt_pk_bf16_f32 v45, v52, v53
	v_cvt_pk_bf16_f32 v26, v38, v39
	v_cvt_pk_bf16_f32 v27, v40, v41
	v_cvt_pk_bf16_f32 v28, v34, v35
	v_cvt_pk_bf16_f32 v29, v36, v37
	v_lshl_add_u64 v[14:15], v[156:157], 0, s[24:25]
	v_cvt_pk_bf16_f32 v10, v22, v23
	v_cvt_pk_bf16_f32 v11, v24, v25
	v_cvt_pk_bf16_f32 v12, v18, v19
	v_cvt_pk_bf16_f32 v13, v20, v21
	v_cvt_pk_bf16_f32 v6, v6, v7
	v_cvt_pk_bf16_f32 v7, v8, v9
	v_cvt_pk_bf16_f32 v8, v2, v3
	v_cvt_pk_bf16_f32 v9, v4, v5
	s_andn2_b64 vcc, exec, s[4:5]
	s_mov_b64 s[4:5], -1
	global_store_dwordx4 v[156:157], v[126:129], off
	global_store_dwordx4 v[110:111], v[106:109], off
	global_store_dwordx4 v[94:95], v[90:93], off
	global_store_dwordx4 v[78:79], v[74:77], off
	global_store_dwordx4 v[78:79], v[70:73], off offset:256
	global_store_dwordx4 v[58:59], v[62:65], off
	global_store_dwordx4 v[48:49], v[42:45], off
	global_store_dwordx4 v[32:33], v[26:29], off
	global_store_dwordx4 v[16:17], v[10:13], off
	global_store_dwordx4 v[14:15], v[6:9], off offset:256
	s_cbranch_vccnz .LBB0_798
	s_andn2_b64 vcc, exec, s[8:9]
	s_cbranch_vccnz .LBB0_797
	s_branch .LBB0_797

; __device__ __forceinline__ unsigned cvt_pk_bf16(float lo, float hi) { const bf16x2_cv v = __builtin_convertvector((f32x2_cv){lo, hi}, bf16x2_cv); return __builtin_bit_cast(unsigned, v); }
; __device__ __forceinline__ float sigmoid_f(float x) { return __builtin_amdgcn_rcpf(1.0f + __expf(-x)); }
; #define PG8_BAR __builtin_amdgcn_s_barrier()
;     __device__ __forceinline__ void operator()(const f32x4 (&acc)[2][2][4][2], const Unit& u, int wr, int wc, int fr, int fq) const {
;         const int row0 = u.pm * BM + wr * 64 + fr; const int col0 = u.pn * HALF + wc * 32 + 8 * fq;
; #pragma unroll
;         for (int ai = 0; ai < 2; ++ai)
; #pragma unroll
;             for (int m = 0; m < 4; ++m) { bf16_t* rowp = O + (size_t)(row0 + ai * HALF + m * 16) * ldc + col0;
;                 float o[8];
; #pragma unroll
;                 for (int n = 0; n < 2; ++n)
; #pragma unroll
;                     for (int j = 0; j < 4; ++j) { const float g = acc[ai][0][m][n][j], up = acc[ai][1][m][n][j]; o[n * 4 + j] = g * sigmoid_f(g) * up; }
;                 u32x4 w; w.x = cvt_pk_bf16(o[0], o[1]); w.y = cvt_pk_bf16(o[2], o[3]); w.z = cvt_pk_bf16(o[4], o[5]); w.w = cvt_pk_bf16(o[6], o[7]);
;                 *(u32x4*)rowp = w; }
; template <class Epi, class Sched, bool ALIGN_EPI = false, bool SP2 = false>
; __device__ __forceinline__ void gemm_phase(PG8_LAS unsigned char* lds, const Gemm g, const Sched& S, const Epi& E) {
;     ...
;         if constexpr (ALIGN_EPI) { if (wr == 0) PG8_BAR; }
.Lpeel_exit_8:
	s_and_b64 vcc, exec, s[8:9]
	s_cbranch_vccz .LBB0_943
	s_and_b64 vcc, exec, s[4:5]
	s_cbranch_vccnz .LBB0_943
	s_barrier
.LBB0_943:
	v_mul_f32_e32 v146, 0xbfb8aa3b, v126
	v_exp_f32_e32 v146, v146
	v_mul_f32_e32 v147, 0xbfb8aa3b, v127
	v_exp_f32_e32 v147, v147
	v_lshl_or_b32 v154, s47, 7, v149
	v_add_f32_e32 v146, 1.0, v146
	v_rcp_f32_e32 v156, v146
	v_add_f32_e32 v146, 1.0, v147
	v_rcp_f32_e32 v157, v146
	v_lshl_add_u32 v153, s24, 8, v1
	v_ashrrev_i32_e32 v155, 31, v154
	v_mov_b64_e32 v[146:147], s[84:85]
	v_pk_mul_f32 v[126:127], v[126:127], v[156:157]
	v_mul_f32_e32 v156, 0xbfb8aa3b, v128
	v_mul_f32_e32 v157, 0xbfb8aa3b, v129
	v_exp_f32_e32 v156, v156
	v_exp_f32_e32 v157, v157
	v_pk_mul_f32 v[118:119], v[126:127], v[118:119]
	v_mad_i64_i32 v[158:159], s[26:27], v153, s46, v[146:147]
	v_add_f32_e32 v126, 1.0, v156
	v_add_f32_e32 v127, 1.0, v157
	v_mul_f32_e32 v156, 0xbfb8aa3b, v122
	v_mul_f32_e32 v157, 0xbfb8aa3b, v123
	v_rcp_f32_e32 v126, v126
	v_rcp_f32_e32 v127, v127
	v_exp_f32_e32 v156, v156
	v_exp_f32_e32 v157, v157
	s_andn2_b64 vcc, exec, s[4:5]
	v_pk_mul_f32 v[126:127], v[128:129], v[126:127]
	v_add_f32_e32 v128, 1.0, v156
	v_add_f32_e32 v129, 1.0, v157
	v_mul_f32_e32 v156, 0xbfb8aa3b, v124
	v_mul_f32_e32 v157, 0xbfb8aa3b, v125
	v_exp_f32_e32 v156, v156
	v_exp_f32_e32 v157, v157
	v_rcp_f32_e32 v128, v128
	v_rcp_f32_e32 v129, v129
	v_add_f32_e32 v156, 1.0, v156
	v_add_f32_e32 v157, 1.0, v157
	v_rcp_f32_e32 v156, v156
	v_rcp_f32_e32 v157, v157
	v_pk_mul_f32 v[122:123], v[122:123], v[128:129]
	v_pk_mul_f32 v[120:121], v[126:127], v[120:121]
	v_pk_mul_f32 v[122:123], v[122:123], v[114:115]
	v_pk_mul_f32 v[114:115], v[124:125], v[156:157]
	s_mov_b64 s[4:5], -1
	v_pk_mul_f32 v[124:125], v[114:115], v[116:117]
	v_cvt_pk_bf16_f32 v117, v120, v121
	v_mul_f32_e32 v120, 0xbfb8aa3b, v110
	v_mul_f32_e32 v121, 0xbfb8aa3b, v111
	v_exp_f32_e32 v120, v120
	v_exp_f32_e32 v121, v121
	v_lshlrev_b64 v[114:115], 1, v[154:155]
	v_lshl_add_u64 v[126:127], v[158:159], 0, v[114:115]
	v_cvt_pk_bf16_f32 v116, v118, v119
	v_cvt_pk_bf16_f32 v118, v122, v123
	v_cvt_pk_bf16_f32 v119, v124, v125
	global_store_dwordx4 v[126:127], v[116:119], off
	s_nop 1
	v_add_f32_e32 v116, 1.0, v120
	v_add_f32_e32 v117, 1.0, v121
	v_rcp_f32_e32 v116, v116
	v_rcp_f32_e32 v117, v117
	v_or_b32_e32 v118, 16, v153
	v_mad_i64_i32 v[118:119], s[26:27], v118, s46, v[146:147]
	v_pk_mul_f32 v[110:111], v[110:111], v[116:117]
	v_mul_f32_e32 v116, 0xbfb8aa3b, v112
	v_mul_f32_e32 v117, 0xbfb8aa3b, v113
	v_exp_f32_e32 v116, v116
	v_exp_f32_e32 v117, v117
	v_pk_mul_f32 v[102:103], v[110:111], v[102:103]
	v_add_f32_e32 v110, 1.0, v116
	v_add_f32_e32 v111, 1.0, v117
	v_mul_f32_e32 v116, 0xbfb8aa3b, v106
	v_mul_f32_e32 v117, 0xbfb8aa3b, v107
	v_rcp_f32_e32 v110, v110
	v_rcp_f32_e32 v111, v111
	v_exp_f32_e32 v116, v116
	v_exp_f32_e32 v117, v117
	v_pk_mul_f32 v[110:111], v[112:113], v[110:111]
	v_add_f32_e32 v112, 1.0, v116
	v_add_f32_e32 v113, 1.0, v117
	v_mul_f32_e32 v116, 0xbfb8aa3b, v108
	v_mul_f32_e32 v117, 0xbfb8aa3b, v109
	v_exp_f32_e32 v116, v116
	v_exp_f32_e32 v117, v117
	v_rcp_f32_e32 v112, v112
	v_rcp_f32_e32 v113, v113
	v_add_f32_e32 v116, 1.0, v116
	v_add_f32_e32 v117, 1.0, v117
	v_rcp_f32_e32 v116, v116
	v_rcp_f32_e32 v117, v117
	v_pk_mul_f32 v[106:107], v[106:107], v[112:113]
	v_pk_mul_f32 v[104:105], v[110:111], v[104:105]
	v_pk_mul_f32 v[106:107], v[106:107], v[98:99]
	v_pk_mul_f32 v[98:99], v[108:109], v[116:117]
	v_lshl_add_u64 v[110:111], v[118:119], 0, v[114:115]
	v_pk_mul_f32 v[108:109], v[98:99], v[100:101]
	v_cvt_pk_bf16_f32 v98, v102, v103
	v_mul_f32_e32 v102, 0xbfb8aa3b, v94
	v_mul_f32_e32 v103, 0xbfb8aa3b, v95
	v_exp_f32_e32 v102, v102
	v_exp_f32_e32 v103, v103
	v_cvt_pk_bf16_f32 v99, v104, v105
	v_cvt_pk_bf16_f32 v100, v106, v107
	v_cvt_pk_bf16_f32 v101, v108, v109
	global_store_dwordx4 v[110:111], v[98:101], off
	s_nop 1
	v_add_f32_e32 v98, 1.0, v102
	v_add_f32_e32 v99, 1.0, v103
	v_rcp_f32_e32 v98, v98
	v_rcp_f32_e32 v99, v99
	v_or_b32_e32 v100, 32, v153
	v_mad_i64_i32 v[100:101], s[26:27], v100, s46, v[146:147]
	v_pk_mul_f32 v[94:95], v[94:95], v[98:99]
	v_mul_f32_e32 v98, 0xbfb8aa3b, v96
	v_mul_f32_e32 v99, 0xbfb8aa3b, v97
	v_exp_f32_e32 v98, v98
	v_exp_f32_e32 v99, v99
	v_pk_mul_f32 v[86:87], v[94:95], v[86:87]
	v_add_f32_e32 v94, 1.0, v98
	v_add_f32_e32 v95, 1.0, v99
	v_mul_f32_e32 v98, 0xbfb8aa3b, v90
	v_mul_f32_e32 v99, 0xbfb8aa3b, v91
	v_rcp_f32_e32 v94, v94
	v_rcp_f32_e32 v95, v95
	v_exp_f32_e32 v98, v98
	v_exp_f32_e32 v99, v99
	v_pk_mul_f32 v[94:95], v[96:97], v[94:95]
	v_add_f32_e32 v96, 1.0, v98
	v_add_f32_e32 v97, 1.0, v99
	v_mul_f32_e32 v98, 0xbfb8aa3b, v92
	v_mul_f32_e32 v99, 0xbfb8aa3b, v93
	v_exp_f32_e32 v98, v98
	v_exp_f32_e32 v99, v99
	v_rcp_f32_e32 v96, v96
	v_rcp_f32_e32 v97, v97
	v_add_f32_e32 v98, 1.0, v98
	v_add_f32_e32 v99, 1.0, v99
	v_rcp_f32_e32 v98, v98
	v_rcp_f32_e32 v99, v99
	v_pk_mul_f32 v[90:91], v[90:91], v[96:97]
	v_pk_mul_f32 v[88:89], v[94:95], v[88:89]
	v_pk_mul_f32 v[90:91], v[90:91], v[82:83]
	v_pk_mul_f32 v[82:83], v[92:93], v[98:99]
	v_lshl_add_u64 v[94:95], v[100:101], 0, v[114:115]
	v_pk_mul_f32 v[92:93], v[82:83], v[84:85]
	v_cvt_pk_bf16_f32 v82, v86, v87
	v_mul_f32_e32 v86, 0xbfb8aa3b, v78
	v_mul_f32_e32 v87, 0xbfb8aa3b, v79
	v_exp_f32_e32 v86, v86
	v_exp_f32_e32 v87, v87
	v_cvt_pk_bf16_f32 v83, v88, v89
	v_cvt_pk_bf16_f32 v84, v90, v91
	v_cvt_pk_bf16_f32 v85, v92, v93
	global_store_dwordx4 v[94:95], v[82:85], off
	s_nop 1
	v_add_f32_e32 v82, 1.0, v86
	v_add_f32_e32 v83, 1.0, v87
	v_rcp_f32_e32 v82, v82
	v_rcp_f32_e32 v83, v83
	v_or_b32_e32 v84, 48, v153
	v_mad_i64_i32 v[84:85], s[26:27], v84, s46, v[146:147]
; __device__ __forceinline__ unsigned cvt_pk_bf16(float lo, float hi) { const bf16x2_cv v = __builtin_convertvector((f32x2_cv){lo, hi}, bf16x2_cv); return __builtin_bit_cast(unsigned, v); }
; __device__ __forceinline__ float sigmoid_f(float x) { return __builtin_amdgcn_rcpf(1.0f + __expf(-x)); }
;     __device__ __forceinline__ void operator()(const f32x4 (&acc)[2][2][4][2], const Unit& u, int wr, int wc, int fr, int fq) const {
;         const int row0 = u.pm * BM + wr * 64 + fr; const int col0 = u.pn * HALF + wc * 32 + 8 * fq;
; #pragma unroll
;         for (int ai = 0; ai < 2; ++ai)
; #pragma unroll
;             for (int m = 0; m < 4; ++m) { bf16_t* rowp = O + (size_t)(row0 + ai * HALF + m * 16) * ldc + col0;
;                 float o[8];
; #pragma unroll
;                 for (int n = 0; n < 2; ++n)
; #pragma unroll
;                     for (int j = 0; j < 4; ++j) { const float g = acc[ai][0][m][n][j], up = acc[ai][1][m][n][j]; o[n * 4 + j] = g * sigmoid_f(g) * up; }
;                 u32x4 w; w.x = cvt_pk_bf16(o[0], o[1]); w.y = cvt_pk_bf16(o[2], o[3]); w.z = cvt_pk_bf16(o[4], o[5]); w.w = cvt_pk_bf16(o[6], o[7]);
;                 *(u32x4*)rowp = w; }
	v_pk_mul_f32 v[78:79], v[78:79], v[82:83]
	v_mul_f32_e32 v82, 0xbfb8aa3b, v80
	v_mul_f32_e32 v83, 0xbfb8aa3b, v81
	v_exp_f32_e32 v82, v82
	v_exp_f32_e32 v83, v83
	v_pk_mul_f32 v[70:71], v[78:79], v[70:71]
	v_add_f32_e32 v78, 1.0, v82
	v_add_f32_e32 v79, 1.0, v83
	v_mul_f32_e32 v82, 0xbfb8aa3b, v74
	v_mul_f32_e32 v83, 0xbfb8aa3b, v75
	v_rcp_f32_e32 v78, v78
	v_rcp_f32_e32 v79, v79
	v_exp_f32_e32 v82, v82
	v_exp_f32_e32 v83, v83
	v_pk_mul_f32 v[78:79], v[80:81], v[78:79]
	v_add_f32_e32 v80, 1.0, v82
	v_add_f32_e32 v81, 1.0, v83
	v_mul_f32_e32 v82, 0xbfb8aa3b, v76
	v_mul_f32_e32 v83, 0xbfb8aa3b, v77
	v_exp_f32_e32 v82, v82
	v_exp_f32_e32 v83, v83
	v_rcp_f32_e32 v80, v80
	v_rcp_f32_e32 v81, v81
	v_add_f32_e32 v82, 1.0, v82
	v_add_f32_e32 v83, 1.0, v83
	v_rcp_f32_e32 v82, v82
	v_rcp_f32_e32 v83, v83
	v_pk_mul_f32 v[74:75], v[74:75], v[80:81]
	v_pk_mul_f32 v[72:73], v[78:79], v[72:73]
	v_pk_mul_f32 v[74:75], v[74:75], v[66:67]
	v_pk_mul_f32 v[66:67], v[76:77], v[82:83]
	v_lshl_add_u64 v[78:79], v[84:85], 0, v[114:115]
	v_pk_mul_f32 v[76:77], v[66:67], v[68:69]
	v_cvt_pk_bf16_f32 v66, v70, v71
	v_mul_f32_e32 v70, 0xbfb8aa3b, v62
	v_mul_f32_e32 v71, 0xbfb8aa3b, v63
	v_exp_f32_e32 v70, v70
	v_exp_f32_e32 v71, v71
	v_cvt_pk_bf16_f32 v67, v72, v73
	v_cvt_pk_bf16_f32 v68, v74, v75
	v_cvt_pk_bf16_f32 v69, v76, v77
	global_store_dwordx4 v[78:79], v[66:69], off
	s_nop 1
	v_add_f32_e32 v66, 1.0, v70
	v_add_f32_e32 v67, 1.0, v71
	v_rcp_f32_e32 v66, v66
	v_rcp_f32_e32 v67, v67
	v_add_u32_e32 v68, 0x80, v153
	v_mad_i64_i32 v[68:69], s[26:27], v68, s46, v[146:147]
	v_pk_mul_f32 v[62:63], v[62:63], v[66:67]
	v_mul_f32_e32 v66, 0xbfb8aa3b, v64
	v_mul_f32_e32 v67, 0xbfb8aa3b, v65
	v_exp_f32_e32 v66, v66
	v_exp_f32_e32 v67, v67
	v_pk_mul_f32 v[54:55], v[62:63], v[54:55]
	v_add_f32_e32 v62, 1.0, v66
	v_add_f32_e32 v63, 1.0, v67
	v_mul_f32_e32 v66, 0xbfb8aa3b, v58
	v_mul_f32_e32 v67, 0xbfb8aa3b, v59
	v_rcp_f32_e32 v62, v62
	v_rcp_f32_e32 v63, v63
	v_exp_f32_e32 v66, v66
	v_exp_f32_e32 v67, v67
	v_pk_mul_f32 v[62:63], v[64:65], v[62:63]
	v_add_f32_e32 v64, 1.0, v66
	v_add_f32_e32 v65, 1.0, v67
	v_mul_f32_e32 v66, 0xbfb8aa3b, v60
	v_mul_f32_e32 v67, 0xbfb8aa3b, v61
	v_exp_f32_e32 v66, v66
	v_exp_f32_e32 v67, v67
	v_rcp_f32_e32 v64, v64
	v_rcp_f32_e32 v65, v65
	v_add_f32_e32 v66, 1.0, v66
	v_add_f32_e32 v67, 1.0, v67
	v_rcp_f32_e32 v66, v66
	v_rcp_f32_e32 v67, v67
	v_pk_mul_f32 v[58:59], v[58:59], v[64:65]
	v_pk_mul_f32 v[56:57], v[62:63], v[56:57]
	v_pk_mul_f32 v[58:59], v[58:59], v[50:51]
	v_pk_mul_f32 v[50:51], v[60:61], v[66:67]
	v_lshl_add_u64 v[62:63], v[68:69], 0, v[114:115]
	v_pk_mul_f32 v[60:61], v[50:51], v[52:53]
	v_cvt_pk_bf16_f32 v50, v54, v55
	v_mul_f32_e32 v54, 0xbfb8aa3b, v46
	v_mul_f32_e32 v55, 0xbfb8aa3b, v47
	v_exp_f32_e32 v54, v54
	v_exp_f32_e32 v55, v55
	v_cvt_pk_bf16_f32 v51, v56, v57
	v_cvt_pk_bf16_f32 v52, v58, v59
	v_cvt_pk_bf16_f32 v53, v60, v61
	global_store_dwordx4 v[62:63], v[50:53], off
	s_nop 1
	v_add_f32_e32 v50, 1.0, v54
	v_add_f32_e32 v51, 1.0, v55
	v_rcp_f32_e32 v50, v50
	v_rcp_f32_e32 v51, v51
	v_add_u32_e32 v52, 0x90, v153
	v_mad_i64_i32 v[52:53], s[26:27], v52, s46, v[146:147]
	v_pk_mul_f32 v[46:47], v[46:47], v[50:51]
	v_mul_f32_e32 v50, 0xbfb8aa3b, v48
	v_mul_f32_e32 v51, 0xbfb8aa3b, v49
	v_exp_f32_e32 v50, v50
	v_exp_f32_e32 v51, v51
	v_pk_mul_f32 v[38:39], v[46:47], v[38:39]
	v_add_f32_e32 v46, 1.0, v50
	v_add_f32_e32 v47, 1.0, v51
	v_mul_f32_e32 v50, 0xbfb8aa3b, v42
	v_mul_f32_e32 v51, 0xbfb8aa3b, v43
	v_rcp_f32_e32 v46, v46
	v_rcp_f32_e32 v47, v47
	v_exp_f32_e32 v50, v50
	v_exp_f32_e32 v51, v51
	v_pk_mul_f32 v[46:47], v[48:49], v[46:47]
	v_add_f32_e32 v48, 1.0, v50
	v_add_f32_e32 v49, 1.0, v51
	v_mul_f32_e32 v50, 0xbfb8aa3b, v44
	v_mul_f32_e32 v51, 0xbfb8aa3b, v45
	v_exp_f32_e32 v50, v50
	v_exp_f32_e32 v51, v51
; __device__ __forceinline__ unsigned cvt_pk_bf16(float lo, float hi) { const bf16x2_cv v = __builtin_convertvector((f32x2_cv){lo, hi}, bf16x2_cv); return __builtin_bit_cast(unsigned, v); }
; __device__ __forceinline__ float sigmoid_f(float x) { return __builtin_amdgcn_rcpf(1.0f + __expf(-x)); }
; #define PG8_BAR __builtin_amdgcn_s_barrier()
;     __device__ __forceinline__ void operator()(const f32x4 (&acc)[2][2][4][2], const Unit& u, int wr, int wc, int fr, int fq) const {
;     ...
;             for (int m = 0; m < 4; ++m) { bf16_t* rowp = O + (size_t)(row0 + ai * HALF + m * 16) * ldc + col0;
;                 float o[8];
; #pragma unroll
;                 for (int n = 0; n < 2; ++n)
; #pragma unroll
;                     for (int j = 0; j < 4; ++j) { const float g = acc[ai][0][m][n][j], up = acc[ai][1][m][n][j]; o[n * 4 + j] = g * sigmoid_f(g) * up; }
;                 u32x4 w; w.x = cvt_pk_bf16(o[0], o[1]); w.y = cvt_pk_bf16(o[2], o[3]); w.z = cvt_pk_bf16(o[4], o[5]); w.w = cvt_pk_bf16(o[6], o[7]);
;                 *(u32x4*)rowp = w; }
; template <class Epi, class Sched, bool ALIGN_EPI = false, bool SP2 = false>
; __device__ __forceinline__ void gemm_phase(PG8_LAS unsigned char* lds, const Gemm g, const Sched& S, const Epi& E) {
;     ...
;         cur = nxt; cA = nA; cB = nB; ++ui;
;         if constexpr (ALIGN_EPI) { if (wr == 1) PG8_BAR; }
	v_rcp_f32_e32 v48, v48
	v_rcp_f32_e32 v49, v49
	v_add_f32_e32 v50, 1.0, v50
	v_add_f32_e32 v51, 1.0, v51
	v_rcp_f32_e32 v50, v50
	v_rcp_f32_e32 v51, v51
	v_pk_mul_f32 v[42:43], v[42:43], v[48:49]
	v_pk_mul_f32 v[40:41], v[46:47], v[40:41]
	v_pk_mul_f32 v[42:43], v[42:43], v[34:35]
	v_pk_mul_f32 v[34:35], v[44:45], v[50:51]
	v_lshl_add_u64 v[46:47], v[52:53], 0, v[114:115]
	v_pk_mul_f32 v[44:45], v[34:35], v[36:37]
	v_cvt_pk_bf16_f32 v34, v38, v39
	v_mul_f32_e32 v38, 0xbfb8aa3b, v30
	v_mul_f32_e32 v39, 0xbfb8aa3b, v31
	v_exp_f32_e32 v38, v38
	v_exp_f32_e32 v39, v39
	v_cvt_pk_bf16_f32 v35, v40, v41
	v_cvt_pk_bf16_f32 v36, v42, v43
	v_cvt_pk_bf16_f32 v37, v44, v45
	global_store_dwordx4 v[46:47], v[34:37], off
	s_nop 1
	v_add_f32_e32 v34, 1.0, v38
	v_add_f32_e32 v35, 1.0, v39
	v_rcp_f32_e32 v34, v34
	v_rcp_f32_e32 v35, v35
	v_add_u32_e32 v36, 0xa0, v153
	v_mad_i64_i32 v[36:37], s[26:27], v36, s46, v[146:147]
	v_pk_mul_f32 v[30:31], v[30:31], v[34:35]
	v_mul_f32_e32 v34, 0xbfb8aa3b, v32
	v_mul_f32_e32 v35, 0xbfb8aa3b, v33
	v_exp_f32_e32 v34, v34
	v_exp_f32_e32 v35, v35
	v_pk_mul_f32 v[22:23], v[30:31], v[22:23]
	v_add_f32_e32 v30, 1.0, v34
	v_add_f32_e32 v31, 1.0, v35
	v_mul_f32_e32 v34, 0xbfb8aa3b, v26
	v_mul_f32_e32 v35, 0xbfb8aa3b, v27
	v_rcp_f32_e32 v30, v30
	v_rcp_f32_e32 v31, v31
	v_exp_f32_e32 v34, v34
	v_exp_f32_e32 v35, v35
	v_pk_mul_f32 v[30:31], v[32:33], v[30:31]
	v_add_f32_e32 v32, 1.0, v34
	v_add_f32_e32 v33, 1.0, v35
	v_mul_f32_e32 v34, 0xbfb8aa3b, v28
	v_mul_f32_e32 v35, 0xbfb8aa3b, v29
	v_exp_f32_e32 v34, v34
	v_exp_f32_e32 v35, v35
	v_rcp_f32_e32 v32, v32
	v_rcp_f32_e32 v33, v33
	v_add_f32_e32 v34, 1.0, v34
	v_add_f32_e32 v35, 1.0, v35
	v_rcp_f32_e32 v34, v34
	v_rcp_f32_e32 v35, v35
	v_pk_mul_f32 v[26:27], v[26:27], v[32:33]
	v_pk_mul_f32 v[24:25], v[30:31], v[24:25]
	v_pk_mul_f32 v[26:27], v[26:27], v[18:19]
	v_pk_mul_f32 v[18:19], v[28:29], v[34:35]
	v_lshl_add_u64 v[30:31], v[36:37], 0, v[114:115]
	v_pk_mul_f32 v[28:29], v[18:19], v[20:21]
	v_cvt_pk_bf16_f32 v18, v22, v23
	v_mul_f32_e32 v22, 0xbfb8aa3b, v14
	v_mul_f32_e32 v23, 0xbfb8aa3b, v15
	v_exp_f32_e32 v22, v22
	v_exp_f32_e32 v23, v23
	v_cvt_pk_bf16_f32 v19, v24, v25
	v_cvt_pk_bf16_f32 v20, v26, v27
	v_cvt_pk_bf16_f32 v21, v28, v29
	global_store_dwordx4 v[30:31], v[18:21], off
	s_nop 1
	v_add_f32_e32 v18, 1.0, v22
	v_add_f32_e32 v19, 1.0, v23
	v_rcp_f32_e32 v18, v18
	v_rcp_f32_e32 v19, v19
	v_add_u32_e32 v20, 0xb0, v153
	v_mad_i64_i32 v[20:21], s[26:27], v20, s46, v[146:147]
	v_pk_mul_f32 v[14:15], v[14:15], v[18:19]
	v_mul_f32_e32 v18, 0xbfb8aa3b, v16
	v_mul_f32_e32 v19, 0xbfb8aa3b, v17
	v_exp_f32_e32 v18, v18
	v_exp_f32_e32 v19, v19
	v_pk_mul_f32 v[6:7], v[14:15], v[6:7]
	v_add_f32_e32 v14, 1.0, v18
	v_add_f32_e32 v15, 1.0, v19
	v_mul_f32_e32 v18, 0xbfb8aa3b, v10
	v_mul_f32_e32 v19, 0xbfb8aa3b, v11
	v_rcp_f32_e32 v14, v14
	v_rcp_f32_e32 v15, v15
	v_exp_f32_e32 v18, v18
	v_exp_f32_e32 v19, v19
	v_pk_mul_f32 v[14:15], v[16:17], v[14:15]
	v_add_f32_e32 v16, 1.0, v18
	v_add_f32_e32 v17, 1.0, v19
	v_mul_f32_e32 v18, 0xbfb8aa3b, v12
	v_mul_f32_e32 v19, 0xbfb8aa3b, v13
	v_exp_f32_e32 v18, v18
	v_exp_f32_e32 v19, v19
	v_rcp_f32_e32 v16, v16
	v_rcp_f32_e32 v17, v17
	v_add_f32_e32 v18, 1.0, v18
	v_add_f32_e32 v19, 1.0, v19
	v_rcp_f32_e32 v18, v18
	v_rcp_f32_e32 v19, v19
	v_pk_mul_f32 v[10:11], v[10:11], v[16:17]
	v_pk_mul_f32 v[8:9], v[14:15], v[8:9]
	v_pk_mul_f32 v[10:11], v[10:11], v[2:3]
	v_pk_mul_f32 v[2:3], v[12:13], v[18:19]
	v_lshl_add_u64 v[14:15], v[20:21], 0, v[114:115]
	v_pk_mul_f32 v[12:13], v[2:3], v[4:5]
	v_cvt_pk_bf16_f32 v2, v6, v7
	v_cvt_pk_bf16_f32 v3, v8, v9
	v_cvt_pk_bf16_f32 v4, v10, v11
	v_cvt_pk_bf16_f32 v5, v12, v13
	global_store_dwordx4 v[14:15], v[2:5], off
	s_cbranch_vccnz .LBB0_936
	s_andn2_b64 vcc, exec, s[0:1]
	s_cbranch_vccnz .LBB0_935
	s_branch .LBB0_935

; __device__ __forceinline__ unsigned cvt_pk_bf16(float lo, float hi) { const bf16x2_cv v = __builtin_convertvector((f32x2_cv){lo, hi}, bf16x2_cv); return __builtin_bit_cast(unsigned, v); }
; __device__ __forceinline__ float sigmoid_f(float x) { return __builtin_amdgcn_rcpf(1.0f + __expf(-x)); }
;     __device__ __forceinline__ void operator()(const f32x4 (&acc)[2][2][4][2], const Unit& u, int wr, int wc, int fr, int fq) const {
;         const int row0 = u.pm * BM + wr * 64 + fr; const int col0 = u.pn * HALF + wc * 32 + 8 * fq;
; #pragma unroll
;         for (int ai = 0; ai < 2; ++ai)
; #pragma unroll
;             for (int m = 0; m < 4; ++m) { bf16_t* rowp = O + (size_t)(row0 + ai * HALF + m * 16) * ldc + col0;
;                 float o[8];
; #pragma unroll
;                 for (int n = 0; n < 2; ++n)
; #pragma unroll
;                     for (int j = 0; j < 4; ++j) { const float g = acc[ai][0][m][n][j], up = acc[ai][1][m][n][j]; o[n * 4 + j] = g * sigmoid_f(g) * up; }
;                 u32x4 w; w.x = cvt_pk_bf16(o[0], o[1]); w.y = cvt_pk_bf16(o[2], o[3]); w.z = cvt_pk_bf16(o[4], o[5]); w.w = cvt_pk_bf16(o[6], o[7]);
;                 *(u32x4*)rowp = w; }
.LBB0_1490:
	v_mul_f32_e32 v146, 0xbfb8aa3b, v126
	v_exp_f32_e32 v146, v146
	v_mul_f32_e32 v147, 0xbfb8aa3b, v127
	v_exp_f32_e32 v147, v147
	v_lshl_or_b32 v154, s45, 7, v149
	v_add_f32_e32 v146, 1.0, v146
	v_rcp_f32_e32 v156, v146
	v_add_f32_e32 v146, 1.0, v147
	v_rcp_f32_e32 v157, v146
	v_lshl_add_u32 v153, s20, 8, v1
	v_ashrrev_i32_e32 v155, 31, v154
	v_mov_b64_e32 v[146:147], s[84:85]
	v_pk_mul_f32 v[126:127], v[126:127], v[156:157]
	v_mul_f32_e32 v156, 0xbfb8aa3b, v128
	v_mul_f32_e32 v157, 0xbfb8aa3b, v129
	v_exp_f32_e32 v156, v156
	v_exp_f32_e32 v157, v157
	v_pk_mul_f32 v[118:119], v[126:127], v[118:119]
	v_mad_i64_i32 v[158:159], s[22:23], v153, s44, v[146:147]
	v_add_f32_e32 v126, 1.0, v156
	v_add_f32_e32 v127, 1.0, v157
	v_mul_f32_e32 v156, 0xbfb8aa3b, v122
	v_mul_f32_e32 v157, 0xbfb8aa3b, v123
	v_rcp_f32_e32 v126, v126
	v_rcp_f32_e32 v127, v127
	v_exp_f32_e32 v156, v156
	v_exp_f32_e32 v157, v157
	s_andn2_b64 vcc, exec, s[4:5]
	v_pk_mul_f32 v[126:127], v[128:129], v[126:127]
	v_add_f32_e32 v128, 1.0, v156
	v_add_f32_e32 v129, 1.0, v157
	v_mul_f32_e32 v156, 0xbfb8aa3b, v124
	v_mul_f32_e32 v157, 0xbfb8aa3b, v125
	v_exp_f32_e32 v156, v156
	v_exp_f32_e32 v157, v157
	v_rcp_f32_e32 v128, v128
	v_rcp_f32_e32 v129, v129
	v_add_f32_e32 v156, 1.0, v156
	v_add_f32_e32 v157, 1.0, v157
	v_rcp_f32_e32 v156, v156
	v_rcp_f32_e32 v157, v157
	v_pk_mul_f32 v[122:123], v[122:123], v[128:129]
	v_pk_mul_f32 v[120:121], v[126:127], v[120:121]
	v_pk_mul_f32 v[122:123], v[122:123], v[114:115]
	v_pk_mul_f32 v[114:115], v[124:125], v[156:157]
	s_mov_b64 s[4:5], -1
	v_pk_mul_f32 v[124:125], v[114:115], v[116:117]
	v_cvt_pk_bf16_f32 v117, v120, v121
	v_mul_f32_e32 v120, 0xbfb8aa3b, v110
	v_mul_f32_e32 v121, 0xbfb8aa3b, v111
	v_exp_f32_e32 v120, v120
	v_exp_f32_e32 v121, v121
	v_lshlrev_b64 v[114:115], 1, v[154:155]
	v_lshl_add_u64 v[126:127], v[158:159], 0, v[114:115]
	v_cvt_pk_bf16_f32 v116, v118, v119
	v_cvt_pk_bf16_f32 v118, v122, v123
	v_cvt_pk_bf16_f32 v119, v124, v125
	global_store_dwordx4 v[126:127], v[116:119], off
	s_nop 1
	v_add_f32_e32 v116, 1.0, v120
	v_add_f32_e32 v117, 1.0, v121
	v_rcp_f32_e32 v116, v116
	v_rcp_f32_e32 v117, v117
	v_or_b32_e32 v118, 16, v153
	v_mad_i64_i32 v[118:119], s[22:23], v118, s44, v[146:147]
	v_pk_mul_f32 v[110:111], v[110:111], v[116:117]
	v_mul_f32_e32 v116, 0xbfb8aa3b, v112
	v_mul_f32_e32 v117, 0xbfb8aa3b, v113
	v_exp_f32_e32 v116, v116
	v_exp_f32_e32 v117, v117
	v_pk_mul_f32 v[102:103], v[110:111], v[102:103]
	v_add_f32_e32 v110, 1.0, v116
	v_add_f32_e32 v111, 1.0, v117
	v_mul_f32_e32 v116, 0xbfb8aa3b, v106
	v_mul_f32_e32 v117, 0xbfb8aa3b, v107
	v_rcp_f32_e32 v110, v110
	v_rcp_f32_e32 v111, v111
	v_exp_f32_e32 v116, v116
	v_exp_f32_e32 v117, v117
	v_pk_mul_f32 v[110:111], v[112:113], v[110:111]
	v_add_f32_e32 v112, 1.0, v116
	v_add_f32_e32 v113, 1.0, v117
	v_mul_f32_e32 v116, 0xbfb8aa3b, v108
	v_mul_f32_e32 v117, 0xbfb8aa3b, v109
	v_exp_f32_e32 v116, v116
	v_exp_f32_e32 v117, v117
	v_rcp_f32_e32 v112, v112
	v_rcp_f32_e32 v113, v113
	v_add_f32_e32 v116, 1.0, v116
	v_add_f32_e32 v117, 1.0, v117
	v_rcp_f32_e32 v116, v116
	v_rcp_f32_e32 v117, v117
	v_pk_mul_f32 v[106:107], v[106:107], v[112:113]
	v_pk_mul_f32 v[104:105], v[110:111], v[104:105]
	v_pk_mul_f32 v[106:107], v[106:107], v[98:99]
	v_pk_mul_f32 v[98:99], v[108:109], v[116:117]
	v_lshl_add_u64 v[110:111], v[118:119], 0, v[114:115]
	v_pk_mul_f32 v[108:109], v[98:99], v[100:101]
	v_cvt_pk_bf16_f32 v98, v102, v103
	v_mul_f32_e32 v102, 0xbfb8aa3b, v94
	v_mul_f32_e32 v103, 0xbfb8aa3b, v95
	v_exp_f32_e32 v102, v102
	v_exp_f32_e32 v103, v103
	v_cvt_pk_bf16_f32 v99, v104, v105
	v_cvt_pk_bf16_f32 v100, v106, v107
	v_cvt_pk_bf16_f32 v101, v108, v109
	global_store_dwordx4 v[110:111], v[98:101], off
	s_nop 1
	v_add_f32_e32 v98, 1.0, v102
	v_add_f32_e32 v99, 1.0, v103
	v_rcp_f32_e32 v98, v98
	v_rcp_f32_e32 v99, v99
	v_or_b32_e32 v100, 32, v153
	v_mad_i64_i32 v[100:101], s[22:23], v100, s44, v[146:147]
	v_pk_mul_f32 v[94:95], v[94:95], v[98:99]
	v_mul_f32_e32 v98, 0xbfb8aa3b, v96
	v_mul_f32_e32 v99, 0xbfb8aa3b, v97
	v_exp_f32_e32 v98, v98
	v_exp_f32_e32 v99, v99
	v_pk_mul_f32 v[86:87], v[94:95], v[86:87]
	v_add_f32_e32 v94, 1.0, v98
	v_add_f32_e32 v95, 1.0, v99
	v_mul_f32_e32 v98, 0xbfb8aa3b, v90
	v_mul_f32_e32 v99, 0xbfb8aa3b, v91
	v_rcp_f32_e32 v94, v94
	v_rcp_f32_e32 v95, v95
	v_exp_f32_e32 v98, v98
	v_exp_f32_e32 v99, v99
	v_pk_mul_f32 v[94:95], v[96:97], v[94:95]
	v_add_f32_e32 v96, 1.0, v98
	v_add_f32_e32 v97, 1.0, v99
	v_mul_f32_e32 v98, 0xbfb8aa3b, v92
	v_mul_f32_e32 v99, 0xbfb8aa3b, v93
	v_exp_f32_e32 v98, v98
	v_exp_f32_e32 v99, v99
	v_rcp_f32_e32 v96, v96
	v_rcp_f32_e32 v97, v97
	v_add_f32_e32 v98, 1.0, v98
	v_add_f32_e32 v99, 1.0, v99
	v_rcp_f32_e32 v98, v98
	v_rcp_f32_e32 v99, v99
	v_pk_mul_f32 v[90:91], v[90:91], v[96:97]
	v_pk_mul_f32 v[88:89], v[94:95], v[88:89]
	v_pk_mul_f32 v[90:91], v[90:91], v[82:83]
	v_pk_mul_f32 v[82:83], v[92:93], v[98:99]
	v_lshl_add_u64 v[94:95], v[100:101], 0, v[114:115]
	v_pk_mul_f32 v[92:93], v[82:83], v[84:85]
	v_cvt_pk_bf16_f32 v82, v86, v87
	v_mul_f32_e32 v86, 0xbfb8aa3b, v78
	v_mul_f32_e32 v87, 0xbfb8aa3b, v79
	v_exp_f32_e32 v86, v86
	v_exp_f32_e32 v87, v87
	v_cvt_pk_bf16_f32 v83, v88, v89
	v_cvt_pk_bf16_f32 v84, v90, v91
	v_cvt_pk_bf16_f32 v85, v92, v93
	global_store_dwordx4 v[94:95], v[82:85], off
	s_nop 1
	v_add_f32_e32 v82, 1.0, v86
	v_add_f32_e32 v83, 1.0, v87
	v_rcp_f32_e32 v82, v82
	v_rcp_f32_e32 v83, v83
	v_or_b32_e32 v84, 48, v153
	v_mad_i64_i32 v[84:85], s[22:23], v84, s44, v[146:147]
	v_pk_mul_f32 v[78:79], v[78:79], v[82:83]
	v_mul_f32_e32 v82, 0xbfb8aa3b, v80
	v_mul_f32_e32 v83, 0xbfb8aa3b, v81
	v_exp_f32_e32 v82, v82
; __device__ __forceinline__ unsigned cvt_pk_bf16(float lo, float hi) { const bf16x2_cv v = __builtin_convertvector((f32x2_cv){lo, hi}, bf16x2_cv); return __builtin_bit_cast(unsigned, v); }
; __device__ __forceinline__ float sigmoid_f(float x) { return __builtin_amdgcn_rcpf(1.0f + __expf(-x)); }
;     __device__ __forceinline__ void operator()(const f32x4 (&acc)[2][2][4][2], const Unit& u, int wr, int wc, int fr, int fq) const {
;     ...
;             for (int m = 0; m < 4; ++m) { bf16_t* rowp = O + (size_t)(row0 + ai * HALF + m * 16) * ldc + col0;
;                 float o[8];
; #pragma unroll
;                 for (int n = 0; n < 2; ++n)
; #pragma unroll
;                     for (int j = 0; j < 4; ++j) { const float g = acc[ai][0][m][n][j], up = acc[ai][1][m][n][j]; o[n * 4 + j] = g * sigmoid_f(g) * up; }
;                 u32x4 w; w.x = cvt_pk_bf16(o[0], o[1]); w.y = cvt_pk_bf16(o[2], o[3]); w.z = cvt_pk_bf16(o[4], o[5]); w.w = cvt_pk_bf16(o[6], o[7]);
;                 *(u32x4*)rowp = w; }
	v_exp_f32_e32 v83, v83
	v_pk_mul_f32 v[70:71], v[78:79], v[70:71]
	v_add_f32_e32 v78, 1.0, v82
	v_add_f32_e32 v79, 1.0, v83
	v_mul_f32_e32 v82, 0xbfb8aa3b, v74
	v_mul_f32_e32 v83, 0xbfb8aa3b, v75
	v_rcp_f32_e32 v78, v78
	v_rcp_f32_e32 v79, v79
	v_exp_f32_e32 v82, v82
	v_exp_f32_e32 v83, v83
	v_pk_mul_f32 v[78:79], v[80:81], v[78:79]
	v_add_f32_e32 v80, 1.0, v82
	v_add_f32_e32 v81, 1.0, v83
	v_mul_f32_e32 v82, 0xbfb8aa3b, v76
	v_mul_f32_e32 v83, 0xbfb8aa3b, v77
	v_exp_f32_e32 v82, v82
	v_exp_f32_e32 v83, v83
	v_rcp_f32_e32 v80, v80
	v_rcp_f32_e32 v81, v81
	v_add_f32_e32 v82, 1.0, v82
	v_add_f32_e32 v83, 1.0, v83
	v_rcp_f32_e32 v82, v82
	v_rcp_f32_e32 v83, v83
	v_pk_mul_f32 v[74:75], v[74:75], v[80:81]
	v_pk_mul_f32 v[72:73], v[78:79], v[72:73]
	v_pk_mul_f32 v[74:75], v[74:75], v[66:67]
	v_pk_mul_f32 v[66:67], v[76:77], v[82:83]
	v_lshl_add_u64 v[78:79], v[84:85], 0, v[114:115]
	v_pk_mul_f32 v[76:77], v[66:67], v[68:69]
	v_cvt_pk_bf16_f32 v66, v70, v71
	v_mul_f32_e32 v70, 0xbfb8aa3b, v62
	v_mul_f32_e32 v71, 0xbfb8aa3b, v63
	v_exp_f32_e32 v70, v70
	v_exp_f32_e32 v71, v71
	v_cvt_pk_bf16_f32 v67, v72, v73
	v_cvt_pk_bf16_f32 v68, v74, v75
	v_cvt_pk_bf16_f32 v69, v76, v77
	global_store_dwordx4 v[78:79], v[66:69], off
	s_nop 1
	v_add_f32_e32 v66, 1.0, v70
	v_add_f32_e32 v67, 1.0, v71
	v_rcp_f32_e32 v66, v66
	v_rcp_f32_e32 v67, v67
	v_add_u32_e32 v68, 0x80, v153
	v_mad_i64_i32 v[68:69], s[22:23], v68, s44, v[146:147]
	v_pk_mul_f32 v[62:63], v[62:63], v[66:67]
	v_mul_f32_e32 v66, 0xbfb8aa3b, v64
	v_mul_f32_e32 v67, 0xbfb8aa3b, v65
	v_exp_f32_e32 v66, v66
	v_exp_f32_e32 v67, v67
	v_pk_mul_f32 v[54:55], v[62:63], v[54:55]
	v_add_f32_e32 v62, 1.0, v66
	v_add_f32_e32 v63, 1.0, v67
	v_mul_f32_e32 v66, 0xbfb8aa3b, v58
	v_mul_f32_e32 v67, 0xbfb8aa3b, v59
	v_rcp_f32_e32 v62, v62
	v_rcp_f32_e32 v63, v63
	v_exp_f32_e32 v66, v66
	v_exp_f32_e32 v67, v67
	v_pk_mul_f32 v[62:63], v[64:65], v[62:63]
	v_add_f32_e32 v64, 1.0, v66
	v_add_f32_e32 v65, 1.0, v67
	v_mul_f32_e32 v66, 0xbfb8aa3b, v60
	v_mul_f32_e32 v67, 0xbfb8aa3b, v61
	v_exp_f32_e32 v66, v66
	v_exp_f32_e32 v67, v67
	v_rcp_f32_e32 v64, v64
	v_rcp_f32_e32 v65, v65
	v_add_f32_e32 v66, 1.0, v66
	v_add_f32_e32 v67, 1.0, v67
	v_rcp_f32_e32 v66, v66
	v_rcp_f32_e32 v67, v67
	v_pk_mul_f32 v[58:59], v[58:59], v[64:65]
	v_pk_mul_f32 v[56:57], v[62:63], v[56:57]
	v_pk_mul_f32 v[58:59], v[58:59], v[50:51]
	v_pk_mul_f32 v[50:51], v[60:61], v[66:67]
	v_lshl_add_u64 v[62:63], v[68:69], 0, v[114:115]
	v_pk_mul_f32 v[60:61], v[50:51], v[52:53]
	v_cvt_pk_bf16_f32 v50, v54, v55
	v_mul_f32_e32 v54, 0xbfb8aa3b, v46
	v_mul_f32_e32 v55, 0xbfb8aa3b, v47
	v_exp_f32_e32 v54, v54
	v_exp_f32_e32 v55, v55
	v_cvt_pk_bf16_f32 v51, v56, v57
	v_cvt_pk_bf16_f32 v52, v58, v59
	v_cvt_pk_bf16_f32 v53, v60, v61
	global_store_dwordx4 v[62:63], v[50:53], off
	s_nop 1
	v_add_f32_e32 v50, 1.0, v54
	v_add_f32_e32 v51, 1.0, v55
	v_rcp_f32_e32 v50, v50
	v_rcp_f32_e32 v51, v51
	v_add_u32_e32 v52, 0x90, v153
	v_mad_i64_i32 v[52:53], s[22:23], v52, s44, v[146:147]
	v_pk_mul_f32 v[46:47], v[46:47], v[50:51]
	v_mul_f32_e32 v50, 0xbfb8aa3b, v48
	v_mul_f32_e32 v51, 0xbfb8aa3b, v49
	v_exp_f32_e32 v50, v50
	v_exp_f32_e32 v51, v51
	v_pk_mul_f32 v[38:39], v[46:47], v[38:39]
	v_add_f32_e32 v46, 1.0, v50
	v_add_f32_e32 v47, 1.0, v51
	v_mul_f32_e32 v50, 0xbfb8aa3b, v42
	v_mul_f32_e32 v51, 0xbfb8aa3b, v43
	v_rcp_f32_e32 v46, v46
	v_rcp_f32_e32 v47, v47
	v_exp_f32_e32 v50, v50
	v_exp_f32_e32 v51, v51
	v_pk_mul_f32 v[46:47], v[48:49], v[46:47]
	v_add_f32_e32 v48, 1.0, v50
	v_add_f32_e32 v49, 1.0, v51
	v_mul_f32_e32 v50, 0xbfb8aa3b, v44
	v_mul_f32_e32 v51, 0xbfb8aa3b, v45
	v_exp_f32_e32 v50, v50
	v_exp_f32_e32 v51, v51
	v_rcp_f32_e32 v48, v48
	v_rcp_f32_e32 v49, v49
	v_add_f32_e32 v50, 1.0, v50
; __device__ __forceinline__ unsigned cvt_pk_bf16(float lo, float hi) { const bf16x2_cv v = __builtin_convertvector((f32x2_cv){lo, hi}, bf16x2_cv); return __builtin_bit_cast(unsigned, v); }
; __device__ __forceinline__ float sigmoid_f(float x) { return __builtin_amdgcn_rcpf(1.0f + __expf(-x)); }
; #define PG8_BAR __builtin_amdgcn_s_barrier()
;     __device__ __forceinline__ void operator()(const f32x4 (&acc)[2][2][4][2], const Unit& u, int wr, int wc, int fr, int fq) const {
;     ...
;             for (int m = 0; m < 4; ++m) { bf16_t* rowp = O + (size_t)(row0 + ai * HALF + m * 16) * ldc + col0;
;                 float o[8];
; #pragma unroll
;                 for (int n = 0; n < 2; ++n)
; #pragma unroll
;                     for (int j = 0; j < 4; ++j) { const float g = acc[ai][0][m][n][j], up = acc[ai][1][m][n][j]; o[n * 4 + j] = g * sigmoid_f(g) * up; }
;                 u32x4 w; w.x = cvt_pk_bf16(o[0], o[1]); w.y = cvt_pk_bf16(o[2], o[3]); w.z = cvt_pk_bf16(o[4], o[5]); w.w = cvt_pk_bf16(o[6], o[7]);
;                 *(u32x4*)rowp = w; }
; template <class Epi, class Sched, bool ALIGN_EPI = false, bool SP2 = false>
; __device__ __forceinline__ void gemm_phase(PG8_LAS unsigned char* lds, const Gemm g, const Sched& S, const Epi& E) {
;     ...
;         cur = nxt; cA = nA; cB = nB; ++ui;
;         if constexpr (ALIGN_EPI) { if (wr == 1) PG8_BAR; }
	v_add_f32_e32 v51, 1.0, v51
	v_rcp_f32_e32 v50, v50
	v_rcp_f32_e32 v51, v51
	v_pk_mul_f32 v[42:43], v[42:43], v[48:49]
	v_pk_mul_f32 v[40:41], v[46:47], v[40:41]
	v_pk_mul_f32 v[42:43], v[42:43], v[34:35]
	v_pk_mul_f32 v[34:35], v[44:45], v[50:51]
	v_lshl_add_u64 v[46:47], v[52:53], 0, v[114:115]
	v_pk_mul_f32 v[44:45], v[34:35], v[36:37]
	v_cvt_pk_bf16_f32 v34, v38, v39
	v_mul_f32_e32 v38, 0xbfb8aa3b, v30
	v_mul_f32_e32 v39, 0xbfb8aa3b, v31
	v_exp_f32_e32 v38, v38
	v_exp_f32_e32 v39, v39
	v_cvt_pk_bf16_f32 v35, v40, v41
	v_cvt_pk_bf16_f32 v36, v42, v43
	v_cvt_pk_bf16_f32 v37, v44, v45
	global_store_dwordx4 v[46:47], v[34:37], off
	s_nop 1
	v_add_f32_e32 v34, 1.0, v38
	v_add_f32_e32 v35, 1.0, v39
	v_rcp_f32_e32 v34, v34
	v_rcp_f32_e32 v35, v35
	v_add_u32_e32 v36, 0xa0, v153
	v_mad_i64_i32 v[36:37], s[22:23], v36, s44, v[146:147]
	v_pk_mul_f32 v[30:31], v[30:31], v[34:35]
	v_mul_f32_e32 v34, 0xbfb8aa3b, v32
	v_mul_f32_e32 v35, 0xbfb8aa3b, v33
	v_exp_f32_e32 v34, v34
	v_exp_f32_e32 v35, v35
	v_pk_mul_f32 v[22:23], v[30:31], v[22:23]
	v_add_f32_e32 v30, 1.0, v34
	v_add_f32_e32 v31, 1.0, v35
	v_mul_f32_e32 v34, 0xbfb8aa3b, v26
	v_mul_f32_e32 v35, 0xbfb8aa3b, v27
	v_rcp_f32_e32 v30, v30
	v_rcp_f32_e32 v31, v31
	v_exp_f32_e32 v34, v34
	v_exp_f32_e32 v35, v35
	v_pk_mul_f32 v[30:31], v[32:33], v[30:31]
	v_add_f32_e32 v32, 1.0, v34
	v_add_f32_e32 v33, 1.0, v35
	v_mul_f32_e32 v34, 0xbfb8aa3b, v28
	v_mul_f32_e32 v35, 0xbfb8aa3b, v29
	v_exp_f32_e32 v34, v34
	v_exp_f32_e32 v35, v35
	v_rcp_f32_e32 v32, v32
	v_rcp_f32_e32 v33, v33
	v_add_f32_e32 v34, 1.0, v34
	v_add_f32_e32 v35, 1.0, v35
	v_rcp_f32_e32 v34, v34
	v_rcp_f32_e32 v35, v35
	v_pk_mul_f32 v[26:27], v[26:27], v[32:33]
	v_pk_mul_f32 v[24:25], v[30:31], v[24:25]
	v_pk_mul_f32 v[26:27], v[26:27], v[18:19]
	v_pk_mul_f32 v[18:19], v[28:29], v[34:35]
	v_lshl_add_u64 v[30:31], v[36:37], 0, v[114:115]
	v_pk_mul_f32 v[28:29], v[18:19], v[20:21]
	v_cvt_pk_bf16_f32 v18, v22, v23
	v_mul_f32_e32 v22, 0xbfb8aa3b, v14
	v_mul_f32_e32 v23, 0xbfb8aa3b, v15
	v_exp_f32_e32 v22, v22
	v_exp_f32_e32 v23, v23
	v_cvt_pk_bf16_f32 v19, v24, v25
	v_cvt_pk_bf16_f32 v20, v26, v27
	v_cvt_pk_bf16_f32 v21, v28, v29
	global_store_dwordx4 v[30:31], v[18:21], off
	s_nop 1
	v_add_f32_e32 v18, 1.0, v22
	v_add_f32_e32 v19, 1.0, v23
	v_rcp_f32_e32 v18, v18
	v_rcp_f32_e32 v19, v19
	v_add_u32_e32 v20, 0xb0, v153
	v_mad_i64_i32 v[20:21], s[22:23], v20, s44, v[146:147]
	v_pk_mul_f32 v[14:15], v[14:15], v[18:19]
	v_mul_f32_e32 v18, 0xbfb8aa3b, v16
	v_mul_f32_e32 v19, 0xbfb8aa3b, v17
	v_exp_f32_e32 v18, v18
	v_exp_f32_e32 v19, v19
	v_pk_mul_f32 v[6:7], v[14:15], v[6:7]
	v_add_f32_e32 v14, 1.0, v18
	v_add_f32_e32 v15, 1.0, v19
	v_mul_f32_e32 v18, 0xbfb8aa3b, v10
	v_mul_f32_e32 v19, 0xbfb8aa3b, v11
	v_rcp_f32_e32 v14, v14
	v_rcp_f32_e32 v15, v15
	v_exp_f32_e32 v18, v18
	v_exp_f32_e32 v19, v19
	v_pk_mul_f32 v[14:15], v[16:17], v[14:15]
	v_add_f32_e32 v16, 1.0, v18
	v_add_f32_e32 v17, 1.0, v19
	v_mul_f32_e32 v18, 0xbfb8aa3b, v12
	v_mul_f32_e32 v19, 0xbfb8aa3b, v13
	v_exp_f32_e32 v18, v18
	v_exp_f32_e32 v19, v19
	v_rcp_f32_e32 v16, v16
	v_rcp_f32_e32 v17, v17
	v_add_f32_e32 v18, 1.0, v18
	v_add_f32_e32 v19, 1.0, v19
	v_rcp_f32_e32 v18, v18
	v_rcp_f32_e32 v19, v19
	v_pk_mul_f32 v[10:11], v[10:11], v[16:17]
	v_pk_mul_f32 v[8:9], v[14:15], v[8:9]
	v_pk_mul_f32 v[10:11], v[10:11], v[2:3]
	v_pk_mul_f32 v[2:3], v[12:13], v[18:19]
	v_lshl_add_u64 v[14:15], v[20:21], 0, v[114:115]
	v_pk_mul_f32 v[12:13], v[2:3], v[4:5]
	v_cvt_pk_bf16_f32 v2, v6, v7
	v_cvt_pk_bf16_f32 v3, v8, v9
	v_cvt_pk_bf16_f32 v4, v10, v11
	v_cvt_pk_bf16_f32 v5, v12, v13
	global_store_dwordx4 v[14:15], v[2:5], off
	s_cbranch_vccnz .LBB0_1483
	s_andn2_b64 vcc, exec, s[0:1]
	s_cbranch_vccnz .LBB0_1482
	s_branch .LBB0_1482

; __device__ __forceinline__ unsigned cvt_pk_bf16(float lo, float hi) { const bf16x2_cv v = __builtin_convertvector((f32x2_cv){lo, hi}, bf16x2_cv); return __builtin_bit_cast(unsigned, v); }
; #define PG8_BAR __builtin_amdgcn_s_barrier()
;     __device__ __forceinline__ void operator()(const f32x4 (&acc)[2][2][4][2], const Unit& u, int wr, int wc, int fr, int fq) const {
;         const int row0 = u.pm * BM + wr * 64 + fr; const int col0 = u.pn * BM + wc * 32 + 8 * fq;
;         f32x4 bv[2][2];
;         if (BIAS) {
; #pragma unroll
;             for (int bj = 0; bj < 2; ++bj)
; #pragma unroll
;                 for (int n = 0; n < 2; ++n) bv[bj][n] = *(const f32x4*)(bias + col0 + bj * HALF + 4 * n); }
; #pragma unroll
;         for (int ai = 0; ai < 2; ++ai)
; #pragma unroll
;             for (int m = 0; m < 4; ++m) { bf16_t* rowp = O + (size_t)(row0 + ai * HALF + m * 16) * ldc + col0;
; #pragma unroll
;                 for (int bj = 0; bj < 2; ++bj) { f32x4 v0 = acc[ai][bj][m][0], v1 = acc[ai][bj][m][1]; if (BIAS) { v0 = v0 + bv[bj][0]; v1 = v1 + bv[bj][1]; }
;                     u32x4 w; w.x = cvt_pk_bf16(v0[0], v0[1]); w.y = cvt_pk_bf16(v0[2], v0[3]); w.z = cvt_pk_bf16(v1[0], v1[1]); w.w = cvt_pk_bf16(v1[2], v1[3]);
;                     *(u32x4*)(rowp + bj * HALF) = w; } }
; template <class Epi, class Sched, bool ALIGN_EPI = false, bool SP2 = false>
; __device__ __forceinline__ void gemm_phase(PG8_LAS unsigned char* lds, const Gemm g, const Sched& S, const Epi& E) {
;     ...
;         cur = nxt; cA = nA; cB = nB; ++ui;
;         if constexpr (ALIGN_EPI) { if (wr == 1) PG8_BAR; }
.LBB0_2262:
	v_lshl_add_u32 v152, s18, 8, v1
	v_lshl_or_b32 v154, s52, 8, v147
	v_ashrrev_i32_e32 v153, 31, v152
	v_ashrrev_i32_e32 v155, 31, v154
	v_lshlrev_b64 v[156:157], 12, v[152:153]
	v_lshl_add_u64 v[156:157], s[84:85], 0, v[156:157]
	v_lshlrev_b64 v[154:155], 1, v[154:155]
	v_lshl_add_u64 v[156:157], v[156:157], 0, v[154:155]
	v_cvt_pk_bf16_f32 v62, v62, v63
	v_cvt_pk_bf16_f32 v63, v64, v65
	v_cvt_pk_bf16_f32 v64, v58, v59
	v_add_co_u32_e32 v58, vcc, s48, v156
	v_cvt_pk_bf16_f32 v70, v70, v71
	v_cvt_pk_bf16_f32 v71, v72, v73
	v_cvt_pk_bf16_f32 v72, v66, v67
	v_lshl_add_u64 v[66:67], v[156:157], 0, s[10:11]
	v_addc_co_u32_e32 v59, vcc, 0, v157, vcc
	v_cvt_pk_bf16_f32 v46, v46, v47
	v_cvt_pk_bf16_f32 v47, v48, v49
	v_cvt_pk_bf16_f32 v48, v42, v43
	v_cvt_pk_bf16_f32 v49, v44, v45
	v_cvt_pk_bf16_f32 v110, v110, v111
	v_cvt_pk_bf16_f32 v111, v112, v113
	v_cvt_pk_bf16_f32 v112, v106, v107
	v_or_b32_e32 v106, 16, v152
	global_store_dwordx4 v[66:67], v[46:49], off offset:256
	v_ashrrev_i32_e32 v107, 31, v106
	v_cvt_pk_bf16_f32 v94, v94, v95
	v_add_co_u32_e32 v48, vcc, s49, v156
	v_cvt_pk_bf16_f32 v95, v96, v97
	v_cvt_pk_bf16_f32 v96, v90, v91
	v_or_b32_e32 v90, 32, v152
	v_lshl_add_u64 v[46:47], v[156:157], 0, s[12:13]
	v_addc_co_u32_e32 v49, vcc, 0, v157, vcc
	v_cvt_pk_bf16_f32 v30, v30, v31
	v_cvt_pk_bf16_f32 v31, v32, v33
	v_cvt_pk_bf16_f32 v32, v26, v27
	v_cvt_pk_bf16_f32 v33, v28, v29
	v_lshlrev_b64 v[106:107], 12, v[106:107]
	v_ashrrev_i32_e32 v91, 31, v90
	v_cvt_pk_bf16_f32 v78, v78, v79
	v_cvt_pk_bf16_f32 v79, v80, v81
	v_cvt_pk_bf16_f32 v80, v74, v75
	v_or_b32_e32 v74, 48, v152
	global_store_dwordx4 v[46:47], v[30:33], off offset:256
	v_cvt_pk_bf16_f32 v113, v108, v109
	v_lshl_add_u64 v[106:107], s[84:85], 0, v[106:107]
	v_add_co_u32_e32 v32, vcc, s50, v156
	v_lshlrev_b64 v[90:91], 12, v[90:91]
	v_ashrrev_i32_e32 v75, 31, v74
	v_lshl_add_u64 v[30:31], v[156:157], 0, s[14:15]
	v_addc_co_u32_e32 v33, vcc, 0, v157, vcc
	v_cvt_pk_bf16_f32 v14, v14, v15
	v_cvt_pk_bf16_f32 v15, v16, v17
	v_cvt_pk_bf16_f32 v16, v10, v11
	v_cvt_pk_bf16_f32 v17, v12, v13
	global_store_dwordx4 v[156:157], v[110:113], off offset:256
	v_cvt_pk_bf16_f32 v97, v92, v93
	v_lshl_add_u64 v[90:91], s[84:85], 0, v[90:91]
	v_lshl_add_u64 v[110:111], v[106:107], 0, v[154:155]
	v_lshlrev_b64 v[74:75], 12, v[74:75]
	global_store_dwordx4 v[30:31], v[14:17], off offset:256
	global_store_dwordx4 v[110:111], v[94:97], off offset:256
	v_cvt_pk_bf16_f32 v81, v76, v77
	v_add_co_u32_e32 v16, vcc, s51, v156
	v_lshl_add_u64 v[94:95], v[90:91], 0, v[154:155]
	v_lshl_add_u64 v[74:75], s[84:85], 0, v[74:75]
	v_addc_co_u32_e32 v17, vcc, 0, v157, vcc
	v_cvt_pk_bf16_f32 v126, v126, v127
	v_cvt_pk_bf16_f32 v127, v128, v129
	v_cvt_pk_bf16_f32 v128, v122, v123
	v_cvt_pk_bf16_f32 v129, v124, v125
	v_cvt_pk_bf16_f32 v106, v118, v119
	v_cvt_pk_bf16_f32 v107, v120, v121
	v_cvt_pk_bf16_f32 v108, v114, v115
	v_cvt_pk_bf16_f32 v109, v116, v117
	v_cvt_pk_bf16_f32 v90, v102, v103
	v_cvt_pk_bf16_f32 v91, v104, v105
	v_cvt_pk_bf16_f32 v92, v98, v99
	v_cvt_pk_bf16_f32 v93, v100, v101
	global_store_dwordx4 v[94:95], v[78:81], off offset:256
	v_cvt_pk_bf16_f32 v76, v82, v83
	v_cvt_pk_bf16_f32 v77, v84, v85
	v_lshl_add_u64 v[78:79], v[74:75], 0, v[154:155]
	v_cvt_pk_bf16_f32 v74, v86, v87
	v_cvt_pk_bf16_f32 v75, v88, v89
	v_cvt_pk_bf16_f32 v73, v68, v69
	v_cvt_pk_bf16_f32 v65, v60, v61
	v_cvt_pk_bf16_f32 v42, v54, v55
	v_cvt_pk_bf16_f32 v43, v56, v57
	v_cvt_pk_bf16_f32 v44, v50, v51
	v_cvt_pk_bf16_f32 v45, v52, v53
	v_cvt_pk_bf16_f32 v26, v38, v39
	v_cvt_pk_bf16_f32 v27, v40, v41
	v_cvt_pk_bf16_f32 v28, v34, v35
	v_cvt_pk_bf16_f32 v29, v36, v37
	v_lshl_add_u64 v[14:15], v[156:157], 0, s[16:17]
	v_cvt_pk_bf16_f32 v10, v22, v23
	v_cvt_pk_bf16_f32 v11, v24, v25
	v_cvt_pk_bf16_f32 v12, v18, v19
	v_cvt_pk_bf16_f32 v13, v20, v21
	v_cvt_pk_bf16_f32 v6, v6, v7
	v_cvt_pk_bf16_f32 v7, v8, v9
	v_cvt_pk_bf16_f32 v8, v2, v3
	v_cvt_pk_bf16_f32 v9, v4, v5
	s_andn2_b64 vcc, exec, s[4:5]
	s_mov_b64 s[4:5], -1
	global_store_dwordx4 v[156:157], v[126:129], off
	global_store_dwordx4 v[110:111], v[106:109], off
	global_store_dwordx4 v[94:95], v[90:93], off
	global_store_dwordx4 v[78:79], v[74:77], off
	global_store_dwordx4 v[78:79], v[70:73], off offset:256
	global_store_dwordx4 v[58:59], v[62:65], off
	global_store_dwordx4 v[48:49], v[42:45], off
	global_store_dwordx4 v[32:33], v[26:29], off
	global_store_dwordx4 v[16:17], v[10:13], off
	global_store_dwordx4 v[14:15], v[6:9], off offset:256
	s_cbranch_vccnz .LBB0_2255
	s_andn2_b64 vcc, exec, s[2:3]
	s_cbranch_vccnz .LBB0_2254
	s_branch .LBB0_2254

; __device__ __forceinline__ unsigned cvt_pk_bf16(float lo, float hi) { const bf16x2_cv v = __builtin_convertvector((f32x2_cv){lo, hi}, bf16x2_cv); return __builtin_bit_cast(unsigned, v); }
; __device__ __forceinline__ float sigmoid_f(float x) { return __builtin_amdgcn_rcpf(1.0f + __expf(-x)); }
;     __device__ __forceinline__ void operator()(const f32x4 (&acc)[2][2][4][2], const Unit& u, int wr, int wc, int fr, int fq) const {
;         const int row0 = u.pm * BM + wr * 64 + fr; const int col0 = u.pn * HALF + wc * 32 + 8 * fq;
; #pragma unroll
;         for (int ai = 0; ai < 2; ++ai)
; #pragma unroll
;             for (int m = 0; m < 4; ++m) { bf16_t* rowp = O + (size_t)(row0 + ai * HALF + m * 16) * ldc + col0;
;                 float o[8];
; #pragma unroll
;                 for (int n = 0; n < 2; ++n)
; #pragma unroll
;                     for (int j = 0; j < 4; ++j) { const float g = acc[ai][0][m][n][j], up = acc[ai][1][m][n][j]; o[n * 4 + j] = g * sigmoid_f(g) * up; }
;                 u32x4 w; w.x = cvt_pk_bf16(o[0], o[1]); w.y = cvt_pk_bf16(o[2], o[3]); w.z = cvt_pk_bf16(o[4], o[5]); w.w = cvt_pk_bf16(o[6], o[7]);
;                 *(u32x4*)rowp = w; }
.LBB0_2390:
	v_mul_f32_e32 v146, 0xbfb8aa3b, v126
	v_exp_f32_e32 v146, v146
	v_mul_f32_e32 v147, 0xbfb8aa3b, v127
	v_exp_f32_e32 v147, v147
	v_lshl_or_b32 v154, s41, 7, v149
	v_add_f32_e32 v146, 1.0, v146
	v_rcp_f32_e32 v156, v146
	v_add_f32_e32 v146, 1.0, v147
	v_rcp_f32_e32 v157, v146
	v_lshl_add_u32 v153, s18, 8, v1
	v_ashrrev_i32_e32 v155, 31, v154
	v_mov_b64_e32 v[146:147], s[84:85]
	v_pk_mul_f32 v[126:127], v[126:127], v[156:157]
	v_mul_f32_e32 v156, 0xbfb8aa3b, v128
	v_mul_f32_e32 v157, 0xbfb8aa3b, v129
	v_exp_f32_e32 v156, v156
	v_exp_f32_e32 v157, v157
	v_pk_mul_f32 v[118:119], v[126:127], v[118:119]
	v_mad_i64_i32 v[158:159], s[20:21], v153, s40, v[146:147]
	v_add_f32_e32 v126, 1.0, v156
	v_add_f32_e32 v127, 1.0, v157
	v_mul_f32_e32 v156, 0xbfb8aa3b, v122
	v_mul_f32_e32 v157, 0xbfb8aa3b, v123
	v_rcp_f32_e32 v126, v126
	v_rcp_f32_e32 v127, v127
	v_exp_f32_e32 v156, v156
	v_exp_f32_e32 v157, v157
	s_andn2_b64 vcc, exec, s[4:5]
	v_pk_mul_f32 v[126:127], v[128:129], v[126:127]
	v_add_f32_e32 v128, 1.0, v156
	v_add_f32_e32 v129, 1.0, v157
	v_mul_f32_e32 v156, 0xbfb8aa3b, v124
	v_mul_f32_e32 v157, 0xbfb8aa3b, v125
	v_exp_f32_e32 v156, v156
	v_exp_f32_e32 v157, v157
	v_rcp_f32_e32 v128, v128
	v_rcp_f32_e32 v129, v129
	v_add_f32_e32 v156, 1.0, v156
	v_add_f32_e32 v157, 1.0, v157
	v_rcp_f32_e32 v156, v156
	v_rcp_f32_e32 v157, v157
	v_pk_mul_f32 v[122:123], v[122:123], v[128:129]
	v_pk_mul_f32 v[120:121], v[126:127], v[120:121]
	v_pk_mul_f32 v[122:123], v[122:123], v[114:115]
	v_pk_mul_f32 v[114:115], v[124:125], v[156:157]
	s_mov_b64 s[4:5], -1
	v_pk_mul_f32 v[124:125], v[114:115], v[116:117]
	v_cvt_pk_bf16_f32 v117, v120, v121
	v_mul_f32_e32 v120, 0xbfb8aa3b, v110
	v_mul_f32_e32 v121, 0xbfb8aa3b, v111
	v_exp_f32_e32 v120, v120
	v_exp_f32_e32 v121, v121
	v_lshlrev_b64 v[114:115], 1, v[154:155]
	v_lshl_add_u64 v[126:127], v[158:159], 0, v[114:115]
	v_cvt_pk_bf16_f32 v116, v118, v119
	v_cvt_pk_bf16_f32 v118, v122, v123
	v_cvt_pk_bf16_f32 v119, v124, v125
	global_store_dwordx4 v[126:127], v[116:119], off
	s_nop 1
	v_add_f32_e32 v116, 1.0, v120
	v_add_f32_e32 v117, 1.0, v121
	v_rcp_f32_e32 v116, v116
	v_rcp_f32_e32 v117, v117
	v_or_b32_e32 v118, 16, v153
	v_mad_i64_i32 v[118:119], s[20:21], v118, s40, v[146:147]
	v_pk_mul_f32 v[110:111], v[110:111], v[116:117]
	v_mul_f32_e32 v116, 0xbfb8aa3b, v112
	v_mul_f32_e32 v117, 0xbfb8aa3b, v113
	v_exp_f32_e32 v116, v116
	v_exp_f32_e32 v117, v117
	v_pk_mul_f32 v[102:103], v[110:111], v[102:103]
	v_add_f32_e32 v110, 1.0, v116
	v_add_f32_e32 v111, 1.0, v117
	v_mul_f32_e32 v116, 0xbfb8aa3b, v106
	v_mul_f32_e32 v117, 0xbfb8aa3b, v107
	v_rcp_f32_e32 v110, v110
	v_rcp_f32_e32 v111, v111
	v_exp_f32_e32 v116, v116
	v_exp_f32_e32 v117, v117
	v_pk_mul_f32 v[110:111], v[112:113], v[110:111]
	v_add_f32_e32 v112, 1.0, v116
	v_add_f32_e32 v113, 1.0, v117
	v_mul_f32_e32 v116, 0xbfb8aa3b, v108
	v_mul_f32_e32 v117, 0xbfb8aa3b, v109
	v_exp_f32_e32 v116, v116
	v_exp_f32_e32 v117, v117
	v_rcp_f32_e32 v112, v112
	v_rcp_f32_e32 v113, v113
	v_add_f32_e32 v116, 1.0, v116
	v_add_f32_e32 v117, 1.0, v117
	v_rcp_f32_e32 v116, v116
	v_rcp_f32_e32 v117, v117
	v_pk_mul_f32 v[106:107], v[106:107], v[112:113]
	v_pk_mul_f32 v[104:105], v[110:111], v[104:105]
	v_pk_mul_f32 v[106:107], v[106:107], v[98:99]
	v_pk_mul_f32 v[98:99], v[108:109], v[116:117]
	v_lshl_add_u64 v[110:111], v[118:119], 0, v[114:115]
	v_pk_mul_f32 v[108:109], v[98:99], v[100:101]
	v_cvt_pk_bf16_f32 v98, v102, v103
	v_mul_f32_e32 v102, 0xbfb8aa3b, v94
	v_mul_f32_e32 v103, 0xbfb8aa3b, v95
	v_exp_f32_e32 v102, v102
	v_exp_f32_e32 v103, v103
	v_cvt_pk_bf16_f32 v99, v104, v105
	v_cvt_pk_bf16_f32 v100, v106, v107
	v_cvt_pk_bf16_f32 v101, v108, v109
	global_store_dwordx4 v[110:111], v[98:101], off
	s_nop 1
	v_add_f32_e32 v98, 1.0, v102
	v_add_f32_e32 v99, 1.0, v103
	v_rcp_f32_e32 v98, v98
	v_rcp_f32_e32 v99, v99
	v_or_b32_e32 v100, 32, v153
	v_mad_i64_i32 v[100:101], s[20:21], v100, s40, v[146:147]
	v_pk_mul_f32 v[94:95], v[94:95], v[98:99]
	v_mul_f32_e32 v98, 0xbfb8aa3b, v96
	v_mul_f32_e32 v99, 0xbfb8aa3b, v97
	v_exp_f32_e32 v98, v98
	v_exp_f32_e32 v99, v99
	v_pk_mul_f32 v[86:87], v[94:95], v[86:87]
	v_add_f32_e32 v94, 1.0, v98
	v_add_f32_e32 v95, 1.0, v99
	v_mul_f32_e32 v98, 0xbfb8aa3b, v90
	v_mul_f32_e32 v99, 0xbfb8aa3b, v91
	v_rcp_f32_e32 v94, v94
	v_rcp_f32_e32 v95, v95
	v_exp_f32_e32 v98, v98
	v_exp_f32_e32 v99, v99
	v_pk_mul_f32 v[94:95], v[96:97], v[94:95]
	v_add_f32_e32 v96, 1.0, v98
	v_add_f32_e32 v97, 1.0, v99
	v_mul_f32_e32 v98, 0xbfb8aa3b, v92
	v_mul_f32_e32 v99, 0xbfb8aa3b, v93
	v_exp_f32_e32 v98, v98
	v_exp_f32_e32 v99, v99
	v_rcp_f32_e32 v96, v96
	v_rcp_f32_e32 v97, v97
	v_add_f32_e32 v98, 1.0, v98
	v_add_f32_e32 v99, 1.0, v99
	v_rcp_f32_e32 v98, v98
	v_rcp_f32_e32 v99, v99
	v_pk_mul_f32 v[90:91], v[90:91], v[96:97]
	v_pk_mul_f32 v[88:89], v[94:95], v[88:89]
	v_pk_mul_f32 v[90:91], v[90:91], v[82:83]
	v_pk_mul_f32 v[82:83], v[92:93], v[98:99]
	v_lshl_add_u64 v[94:95], v[100:101], 0, v[114:115]
	v_pk_mul_f32 v[92:93], v[82:83], v[84:85]
	v_cvt_pk_bf16_f32 v82, v86, v87
	v_mul_f32_e32 v86, 0xbfb8aa3b, v78
	v_mul_f32_e32 v87, 0xbfb8aa3b, v79
	v_exp_f32_e32 v86, v86
	v_exp_f32_e32 v87, v87
	v_cvt_pk_bf16_f32 v83, v88, v89
	v_cvt_pk_bf16_f32 v84, v90, v91
	v_cvt_pk_bf16_f32 v85, v92, v93
	global_store_dwordx4 v[94:95], v[82:85], off
	s_nop 1
	v_add_f32_e32 v82, 1.0, v86
	v_add_f32_e32 v83, 1.0, v87
	v_rcp_f32_e32 v82, v82
	v_rcp_f32_e32 v83, v83
	v_or_b32_e32 v84, 48, v153
	v_mad_i64_i32 v[84:85], s[20:21], v84, s40, v[146:147]
	v_pk_mul_f32 v[78:79], v[78:79], v[82:83]
	v_mul_f32_e32 v82, 0xbfb8aa3b, v80
	v_mul_f32_e32 v83, 0xbfb8aa3b, v81
	v_exp_f32_e32 v82, v82
; __device__ __forceinline__ unsigned cvt_pk_bf16(float lo, float hi) { const bf16x2_cv v = __builtin_convertvector((f32x2_cv){lo, hi}, bf16x2_cv); return __builtin_bit_cast(unsigned, v); }
; __device__ __forceinline__ float sigmoid_f(float x) { return __builtin_amdgcn_rcpf(1.0f + __expf(-x)); }
;     __device__ __forceinline__ void operator()(const f32x4 (&acc)[2][2][4][2], const Unit& u, int wr, int wc, int fr, int fq) const {
;     ...
;             for (int m = 0; m < 4; ++m) { bf16_t* rowp = O + (size_t)(row0 + ai * HALF + m * 16) * ldc + col0;
;                 float o[8];
; #pragma unroll
;                 for (int n = 0; n < 2; ++n)
; #pragma unroll
;                     for (int j = 0; j < 4; ++j) { const float g = acc[ai][0][m][n][j], up = acc[ai][1][m][n][j]; o[n * 4 + j] = g * sigmoid_f(g) * up; }
;                 u32x4 w; w.x = cvt_pk_bf16(o[0], o[1]); w.y = cvt_pk_bf16(o[2], o[3]); w.z = cvt_pk_bf16(o[4], o[5]); w.w = cvt_pk_bf16(o[6], o[7]);
;                 *(u32x4*)rowp = w; }
	v_exp_f32_e32 v83, v83
	v_pk_mul_f32 v[70:71], v[78:79], v[70:71]
	v_add_f32_e32 v78, 1.0, v82
	v_add_f32_e32 v79, 1.0, v83
	v_mul_f32_e32 v82, 0xbfb8aa3b, v74
	v_mul_f32_e32 v83, 0xbfb8aa3b, v75
	v_rcp_f32_e32 v78, v78
	v_rcp_f32_e32 v79, v79
	v_exp_f32_e32 v82, v82
	v_exp_f32_e32 v83, v83
	v_pk_mul_f32 v[78:79], v[80:81], v[78:79]
	v_add_f32_e32 v80, 1.0, v82
	v_add_f32_e32 v81, 1.0, v83
	v_mul_f32_e32 v82, 0xbfb8aa3b, v76
	v_mul_f32_e32 v83, 0xbfb8aa3b, v77
	v_exp_f32_e32 v82, v82
	v_exp_f32_e32 v83, v83
	v_rcp_f32_e32 v80, v80
	v_rcp_f32_e32 v81, v81
	v_add_f32_e32 v82, 1.0, v82
	v_add_f32_e32 v83, 1.0, v83
	v_rcp_f32_e32 v82, v82
	v_rcp_f32_e32 v83, v83
	v_pk_mul_f32 v[74:75], v[74:75], v[80:81]
	v_pk_mul_f32 v[72:73], v[78:79], v[72:73]
	v_pk_mul_f32 v[74:75], v[74:75], v[66:67]
	v_pk_mul_f32 v[66:67], v[76:77], v[82:83]
	v_lshl_add_u64 v[78:79], v[84:85], 0, v[114:115]
	v_pk_mul_f32 v[76:77], v[66:67], v[68:69]
	v_cvt_pk_bf16_f32 v66, v70, v71
	v_mul_f32_e32 v70, 0xbfb8aa3b, v62
	v_mul_f32_e32 v71, 0xbfb8aa3b, v63
	v_exp_f32_e32 v70, v70
	v_exp_f32_e32 v71, v71
	v_cvt_pk_bf16_f32 v67, v72, v73
	v_cvt_pk_bf16_f32 v68, v74, v75
	v_cvt_pk_bf16_f32 v69, v76, v77
	global_store_dwordx4 v[78:79], v[66:69], off
	s_nop 1
	v_add_f32_e32 v66, 1.0, v70
	v_add_f32_e32 v67, 1.0, v71
	v_rcp_f32_e32 v66, v66
	v_rcp_f32_e32 v67, v67
	v_add_u32_e32 v68, 0x80, v153
	v_mad_i64_i32 v[68:69], s[20:21], v68, s40, v[146:147]
	v_pk_mul_f32 v[62:63], v[62:63], v[66:67]
	v_mul_f32_e32 v66, 0xbfb8aa3b, v64
	v_mul_f32_e32 v67, 0xbfb8aa3b, v65
	v_exp_f32_e32 v66, v66
	v_exp_f32_e32 v67, v67
	v_pk_mul_f32 v[54:55], v[62:63], v[54:55]
	v_add_f32_e32 v62, 1.0, v66
	v_add_f32_e32 v63, 1.0, v67
	v_mul_f32_e32 v66, 0xbfb8aa3b, v58
	v_mul_f32_e32 v67, 0xbfb8aa3b, v59
	v_rcp_f32_e32 v62, v62
	v_rcp_f32_e32 v63, v63
	v_exp_f32_e32 v66, v66
	v_exp_f32_e32 v67, v67
	v_pk_mul_f32 v[62:63], v[64:65], v[62:63]
	v_add_f32_e32 v64, 1.0, v66
	v_add_f32_e32 v65, 1.0, v67
	v_mul_f32_e32 v66, 0xbfb8aa3b, v60
	v_mul_f32_e32 v67, 0xbfb8aa3b, v61
	v_exp_f32_e32 v66, v66
	v_exp_f32_e32 v67, v67
	v_rcp_f32_e32 v64, v64
	v_rcp_f32_e32 v65, v65
	v_add_f32_e32 v66, 1.0, v66
	v_add_f32_e32 v67, 1.0, v67
	v_rcp_f32_e32 v66, v66
	v_rcp_f32_e32 v67, v67
	v_pk_mul_f32 v[58:59], v[58:59], v[64:65]
	v_pk_mul_f32 v[56:57], v[62:63], v[56:57]
	v_pk_mul_f32 v[58:59], v[58:59], v[50:51]
	v_pk_mul_f32 v[50:51], v[60:61], v[66:67]
	v_lshl_add_u64 v[62:63], v[68:69], 0, v[114:115]
	v_pk_mul_f32 v[60:61], v[50:51], v[52:53]
	v_cvt_pk_bf16_f32 v50, v54, v55
	v_mul_f32_e32 v54, 0xbfb8aa3b, v46
	v_mul_f32_e32 v55, 0xbfb8aa3b, v47
	v_exp_f32_e32 v54, v54
	v_exp_f32_e32 v55, v55
	v_cvt_pk_bf16_f32 v51, v56, v57
	v_cvt_pk_bf16_f32 v52, v58, v59
	v_cvt_pk_bf16_f32 v53, v60, v61
	global_store_dwordx4 v[62:63], v[50:53], off
	s_nop 1
	v_add_f32_e32 v50, 1.0, v54
	v_add_f32_e32 v51, 1.0, v55
	v_rcp_f32_e32 v50, v50
	v_rcp_f32_e32 v51, v51
	v_add_u32_e32 v52, 0x90, v153
	v_mad_i64_i32 v[52:53], s[20:21], v52, s40, v[146:147]
	v_pk_mul_f32 v[46:47], v[46:47], v[50:51]
	v_mul_f32_e32 v50, 0xbfb8aa3b, v48
	v_mul_f32_e32 v51, 0xbfb8aa3b, v49
	v_exp_f32_e32 v50, v50
	v_exp_f32_e32 v51, v51
	v_pk_mul_f32 v[38:39], v[46:47], v[38:39]
	v_add_f32_e32 v46, 1.0, v50
	v_add_f32_e32 v47, 1.0, v51
	v_mul_f32_e32 v50, 0xbfb8aa3b, v42
	v_mul_f32_e32 v51, 0xbfb8aa3b, v43
	v_rcp_f32_e32 v46, v46
	v_rcp_f32_e32 v47, v47
	v_exp_f32_e32 v50, v50
	v_exp_f32_e32 v51, v51
	v_pk_mul_f32 v[46:47], v[48:49], v[46:47]
	v_add_f32_e32 v48, 1.0, v50
	v_add_f32_e32 v49, 1.0, v51
	v_mul_f32_e32 v50, 0xbfb8aa3b, v44
	v_mul_f32_e32 v51, 0xbfb8aa3b, v45
	v_exp_f32_e32 v50, v50
	v_exp_f32_e32 v51, v51
	v_rcp_f32_e32 v48, v48
	v_rcp_f32_e32 v49, v49
	v_add_f32_e32 v50, 1.0, v50
; __device__ __forceinline__ unsigned cvt_pk_bf16(float lo, float hi) { const bf16x2_cv v = __builtin_convertvector((f32x2_cv){lo, hi}, bf16x2_cv); return __builtin_bit_cast(unsigned, v); }
; __device__ __forceinline__ float sigmoid_f(float x) { return __builtin_amdgcn_rcpf(1.0f + __expf(-x)); }
; #define PG8_BAR __builtin_amdgcn_s_barrier()
;     __device__ __forceinline__ void operator()(const f32x4 (&acc)[2][2][4][2], const Unit& u, int wr, int wc, int fr, int fq) const {
;     ...
;             for (int m = 0; m < 4; ++m) { bf16_t* rowp = O + (size_t)(row0 + ai * HALF + m * 16) * ldc + col0;
;                 float o[8];
; #pragma unroll
;                 for (int n = 0; n < 2; ++n)
; #pragma unroll
;                     for (int j = 0; j < 4; ++j) { const float g = acc[ai][0][m][n][j], up = acc[ai][1][m][n][j]; o[n * 4 + j] = g * sigmoid_f(g) * up; }
;                 u32x4 w; w.x = cvt_pk_bf16(o[0], o[1]); w.y = cvt_pk_bf16(o[2], o[3]); w.z = cvt_pk_bf16(o[4], o[5]); w.w = cvt_pk_bf16(o[6], o[7]);
;                 *(u32x4*)rowp = w; }
; template <class Epi, class Sched, bool ALIGN_EPI = false, bool SP2 = false>
; __device__ __forceinline__ void gemm_phase(PG8_LAS unsigned char* lds, const Gemm g, const Sched& S, const Epi& E) {
;     ...
;         cur = nxt; cA = nA; cB = nB; ++ui;
;         if constexpr (ALIGN_EPI) { if (wr == 1) PG8_BAR; }
	v_add_f32_e32 v51, 1.0, v51
	v_rcp_f32_e32 v50, v50
	v_rcp_f32_e32 v51, v51
	v_pk_mul_f32 v[42:43], v[42:43], v[48:49]
	v_pk_mul_f32 v[40:41], v[46:47], v[40:41]
	v_pk_mul_f32 v[42:43], v[42:43], v[34:35]
	v_pk_mul_f32 v[34:35], v[44:45], v[50:51]
	v_lshl_add_u64 v[46:47], v[52:53], 0, v[114:115]
	v_pk_mul_f32 v[44:45], v[34:35], v[36:37]
	v_cvt_pk_bf16_f32 v34, v38, v39
	v_mul_f32_e32 v38, 0xbfb8aa3b, v30
	v_mul_f32_e32 v39, 0xbfb8aa3b, v31
	v_exp_f32_e32 v38, v38
	v_exp_f32_e32 v39, v39
	v_cvt_pk_bf16_f32 v35, v40, v41
	v_cvt_pk_bf16_f32 v36, v42, v43
	v_cvt_pk_bf16_f32 v37, v44, v45
	global_store_dwordx4 v[46:47], v[34:37], off
	s_nop 1
	v_add_f32_e32 v34, 1.0, v38
	v_add_f32_e32 v35, 1.0, v39
	v_rcp_f32_e32 v34, v34
	v_rcp_f32_e32 v35, v35
	v_add_u32_e32 v36, 0xa0, v153
	v_mad_i64_i32 v[36:37], s[20:21], v36, s40, v[146:147]
	v_pk_mul_f32 v[30:31], v[30:31], v[34:35]
	v_mul_f32_e32 v34, 0xbfb8aa3b, v32
	v_mul_f32_e32 v35, 0xbfb8aa3b, v33
	v_exp_f32_e32 v34, v34
	v_exp_f32_e32 v35, v35
	v_pk_mul_f32 v[22:23], v[30:31], v[22:23]
	v_add_f32_e32 v30, 1.0, v34
	v_add_f32_e32 v31, 1.0, v35
	v_mul_f32_e32 v34, 0xbfb8aa3b, v26
	v_mul_f32_e32 v35, 0xbfb8aa3b, v27
	v_rcp_f32_e32 v30, v30
	v_rcp_f32_e32 v31, v31
	v_exp_f32_e32 v34, v34
	v_exp_f32_e32 v35, v35
	v_pk_mul_f32 v[30:31], v[32:33], v[30:31]
	v_add_f32_e32 v32, 1.0, v34
	v_add_f32_e32 v33, 1.0, v35
	v_mul_f32_e32 v34, 0xbfb8aa3b, v28
	v_mul_f32_e32 v35, 0xbfb8aa3b, v29
	v_exp_f32_e32 v34, v34
	v_exp_f32_e32 v35, v35
	v_rcp_f32_e32 v32, v32
	v_rcp_f32_e32 v33, v33
	v_add_f32_e32 v34, 1.0, v34
	v_add_f32_e32 v35, 1.0, v35
	v_rcp_f32_e32 v34, v34
	v_rcp_f32_e32 v35, v35
	v_pk_mul_f32 v[26:27], v[26:27], v[32:33]
	v_pk_mul_f32 v[24:25], v[30:31], v[24:25]
	v_pk_mul_f32 v[26:27], v[26:27], v[18:19]
	v_pk_mul_f32 v[18:19], v[28:29], v[34:35]
	v_lshl_add_u64 v[30:31], v[36:37], 0, v[114:115]
	v_pk_mul_f32 v[28:29], v[18:19], v[20:21]
	v_cvt_pk_bf16_f32 v18, v22, v23
	v_mul_f32_e32 v22, 0xbfb8aa3b, v14
	v_mul_f32_e32 v23, 0xbfb8aa3b, v15
	v_exp_f32_e32 v22, v22
	v_exp_f32_e32 v23, v23
	v_cvt_pk_bf16_f32 v19, v24, v25
	v_cvt_pk_bf16_f32 v20, v26, v27
	v_cvt_pk_bf16_f32 v21, v28, v29
	global_store_dwordx4 v[30:31], v[18:21], off
	s_nop 1
	v_add_f32_e32 v18, 1.0, v22
	v_add_f32_e32 v19, 1.0, v23
	v_rcp_f32_e32 v18, v18
	v_rcp_f32_e32 v19, v19
	v_add_u32_e32 v20, 0xb0, v153
	v_mad_i64_i32 v[20:21], s[20:21], v20, s40, v[146:147]
	v_pk_mul_f32 v[14:15], v[14:15], v[18:19]
	v_mul_f32_e32 v18, 0xbfb8aa3b, v16
	v_mul_f32_e32 v19, 0xbfb8aa3b, v17
	v_exp_f32_e32 v18, v18
	v_exp_f32_e32 v19, v19
	v_pk_mul_f32 v[6:7], v[14:15], v[6:7]
	v_add_f32_e32 v14, 1.0, v18
	v_add_f32_e32 v15, 1.0, v19
	v_mul_f32_e32 v18, 0xbfb8aa3b, v10
	v_mul_f32_e32 v19, 0xbfb8aa3b, v11
	v_rcp_f32_e32 v14, v14
	v_rcp_f32_e32 v15, v15
	v_exp_f32_e32 v18, v18
	v_exp_f32_e32 v19, v19
	v_pk_mul_f32 v[14:15], v[16:17], v[14:15]
	v_add_f32_e32 v16, 1.0, v18
	v_add_f32_e32 v17, 1.0, v19
	v_mul_f32_e32 v18, 0xbfb8aa3b, v12
	v_mul_f32_e32 v19, 0xbfb8aa3b, v13
	v_exp_f32_e32 v18, v18
	v_exp_f32_e32 v19, v19
	v_rcp_f32_e32 v16, v16
	v_rcp_f32_e32 v17, v17
	v_add_f32_e32 v18, 1.0, v18
	v_add_f32_e32 v19, 1.0, v19
	v_rcp_f32_e32 v18, v18
	v_rcp_f32_e32 v19, v19
	v_pk_mul_f32 v[10:11], v[10:11], v[16:17]
	v_pk_mul_f32 v[8:9], v[14:15], v[8:9]
	v_pk_mul_f32 v[10:11], v[10:11], v[2:3]
	v_pk_mul_f32 v[2:3], v[12:13], v[18:19]
	v_lshl_add_u64 v[14:15], v[20:21], 0, v[114:115]
	v_pk_mul_f32 v[12:13], v[2:3], v[4:5]
	v_cvt_pk_bf16_f32 v2, v6, v7
	v_cvt_pk_bf16_f32 v3, v8, v9
	v_cvt_pk_bf16_f32 v4, v10, v11
	v_cvt_pk_bf16_f32 v5, v12, v13
	global_store_dwordx4 v[14:15], v[2:5], off
	s_cbranch_vccnz .LBB0_2383
	s_andn2_b64 vcc, exec, s[0:1]
	s_cbranch_vccnz .LBB0_2382
	s_branch .LBB0_2382

; #define PG8_BAR __builtin_amdgcn_s_barrier()
;     __device__ __forceinline__ void operator()(const f32x4 (&acc)[2][2][4][2], const Unit& u, int wr, int wc, int fr, int fq) const {
;         const int row0 = u.pm * BM + wr * 64 + fr; const int col0 = u.pn * BM + wc * 32 + 8 * fq;
;         f32x4 bv[2][2];
;         if (BIAS) {
; #pragma unroll
;             for (int bj = 0; bj < 2; ++bj)
; #pragma unroll
;                 for (int n = 0; n < 2; ++n) bv[bj][n] = *(const f32x4*)(bias + col0 + bj * HALF + 4 * n); }
; #pragma unroll
;         for (int ai = 0; ai < 2; ++ai)
; #pragma unroll
;             for (int m = 0; m < 4; ++m) { bf16_t* rowp = O + (size_t)(row0 + ai * HALF + m * 16) * ldc + col0;
; template <class Epi, class Sched, bool ALIGN_EPI = false, bool SP2 = false>
; __device__ __forceinline__ void gemm_phase(PG8_LAS unsigned char* lds, const Gemm g, const Sched& S, const Epi& E) {
;     ...
;         if constexpr (ALIGN_EPI) { if (wr == 0) PG8_BAR; }
;         if constexpr (!Epi::AFTER_DRAIN) { E(acc, cur, wr, wc, fr, fq); S.done(cur); }
.Lpeel_exit_28:
	s_and_b64 vcc, exec, s[10:11]
	s_cbranch_vccz .LBB0_2618
	s_and_b64 vcc, exec, s[4:5]
	s_cbranch_vccnz .LBB0_2618
	s_barrier
.LBB0_2618:
	v_lshl_or_b32 v170, s43, 8, v165
	v_ashrrev_i32_e32 v171, 31, v170
	v_lshl_add_u64 v[130:131], v[170:171], 2, s[2:3]
	global_load_dwordx4 v[142:145], v[130:131], off
	global_load_dwordx4 v[138:141], v[130:131], off offset:16
	global_load_dwordx4 v[134:137], v[130:131], off offset:512
	s_nop 0
	global_load_dwordx4 v[130:133], v[130:131], off offset:528
	v_lshl_add_u32 v169, s20, 8, v1
	v_mov_b64_e32 v[162:163], s[84:85]
	v_mad_i64_i32 v[172:173], s[22:23], v169, s42, v[162:163]
	v_or_b32_e32 v174, 16, v169
	v_or_b32_e32 v176, 32, v169
	v_lshlrev_b64 v[170:171], 1, v[170:171]
	v_or_b32_e32 v178, 48, v169
	v_mad_i64_i32 v[174:175], s[22:23], v174, s42, v[162:163]
	v_mad_i64_i32 v[176:177], s[22:23], v176, s42, v[162:163]
	v_lshl_add_u64 v[172:173], v[172:173], 0, v[170:171]
	v_mad_i64_i32 v[178:179], s[22:23], v178, s42, v[162:163]
	v_lshl_add_u64 v[174:175], v[174:175], 0, v[170:171]
	v_lshl_add_u64 v[176:177], v[176:177], 0, v[170:171]
	v_lshl_add_u64 v[178:179], v[178:179], 0, v[170:171]
	s_andn2_b64 vcc, exec, s[4:5]
	s_mov_b64 s[4:5], -1
	s_waitcnt vmcnt(0)
; __device__ __forceinline__ unsigned cvt_pk_bf16(float lo, float hi) { const bf16x2_cv v = __builtin_convertvector((f32x2_cv){lo, hi}, bf16x2_cv); return __builtin_bit_cast(unsigned, v); }
; #define PG8_BAR __builtin_amdgcn_s_barrier()
;     __device__ __forceinline__ void operator()(const f32x4 (&acc)[2][2][4][2], const Unit& u, int wr, int wc, int fr, int fq) const {
;     ...
;             for (int m = 0; m < 4; ++m) { bf16_t* rowp = O + (size_t)(row0 + ai * HALF + m * 16) * ldc + col0;
; #pragma unroll
;                 for (int bj = 0; bj < 2; ++bj) { f32x4 v0 = acc[ai][bj][m][0], v1 = acc[ai][bj][m][1]; if (BIAS) { v0 = v0 + bv[bj][0]; v1 = v1 + bv[bj][1]; }
;                     u32x4 w; w.x = cvt_pk_bf16(v0[0], v0[1]); w.y = cvt_pk_bf16(v0[2], v0[3]); w.z = cvt_pk_bf16(v1[0], v1[1]); w.w = cvt_pk_bf16(v1[2], v1[3]);
;                     *(u32x4*)(rowp + bj * HALF) = w; } }
; template <class Epi, class Sched, bool ALIGN_EPI = false, bool SP2 = false>
; __device__ __forceinline__ void gemm_phase(PG8_LAS unsigned char* lds, const Gemm g, const Sched& S, const Epi& E) {
;     ...
;         cur = nxt; cA = nA; cB = nB; ++ui;
;         if constexpr (ALIGN_EPI) { if (wr == 1) PG8_BAR; }
	v_pk_add_f32 v[128:129], v[128:129], v[144:145]
	v_pk_add_f32 v[126:127], v[126:127], v[142:143]
	v_pk_add_f32 v[124:125], v[124:125], v[140:141]
	v_pk_add_f32 v[122:123], v[122:123], v[138:139]
	v_pk_add_f32 v[108:109], v[108:109], v[136:137]
	v_pk_add_f32 v[106:107], v[106:107], v[134:135]
	v_pk_add_f32 v[100:101], v[100:101], v[132:133]
	v_pk_add_f32 v[98:99], v[98:99], v[130:131]
	v_pk_add_f32 v[120:121], v[120:121], v[144:145]
	v_pk_add_f32 v[118:119], v[118:119], v[142:143]
	v_pk_add_f32 v[116:117], v[116:117], v[140:141]
	v_pk_add_f32 v[114:115], v[114:115], v[138:139]
	v_pk_add_f32 v[92:93], v[92:93], v[136:137]
	v_pk_add_f32 v[90:91], v[90:91], v[134:135]
	v_pk_add_f32 v[180:181], v[84:85], v[132:133]
	v_pk_add_f32 v[182:183], v[82:83], v[130:131]
	v_pk_add_f32 v[112:113], v[112:113], v[144:145]
	v_pk_add_f32 v[110:111], v[110:111], v[142:143]
	v_pk_add_f32 v[104:105], v[104:105], v[140:141]
	v_pk_add_f32 v[102:103], v[102:103], v[138:139]
	v_pk_add_f32 v[184:185], v[80:81], v[136:137]
	v_pk_add_f32 v[186:187], v[78:79], v[134:135]
	v_pk_add_f32 v[188:189], v[76:77], v[132:133]
	v_pk_add_f32 v[190:191], v[74:75], v[130:131]
	v_cvt_pk_bf16_f32 v74, v126, v127
	v_cvt_pk_bf16_f32 v75, v128, v129
	v_cvt_pk_bf16_f32 v76, v122, v123
	v_cvt_pk_bf16_f32 v77, v124, v125
	v_pk_add_f32 v[192:193], v[96:97], v[144:145]
	v_pk_add_f32 v[194:195], v[94:95], v[142:143]
	v_pk_add_f32 v[196:197], v[88:89], v[140:141]
	v_pk_add_f32 v[198:199], v[86:87], v[138:139]
	v_cvt_pk_bf16_f32 v78, v106, v107
	v_cvt_pk_bf16_f32 v79, v108, v109
	v_cvt_pk_bf16_f32 v80, v98, v99
	v_cvt_pk_bf16_f32 v81, v100, v101
	v_cvt_pk_bf16_f32 v82, v118, v119
	v_cvt_pk_bf16_f32 v83, v120, v121
	v_cvt_pk_bf16_f32 v84, v114, v115
	v_cvt_pk_bf16_f32 v85, v116, v117
	v_cvt_pk_bf16_f32 v86, v90, v91
	v_cvt_pk_bf16_f32 v87, v92, v93
	v_cvt_pk_bf16_f32 v88, v182, v183
	v_cvt_pk_bf16_f32 v89, v180, v181
	v_cvt_pk_bf16_f32 v90, v110, v111
	v_cvt_pk_bf16_f32 v91, v112, v113
	v_cvt_pk_bf16_f32 v92, v102, v103
	v_cvt_pk_bf16_f32 v93, v104, v105
	v_cvt_pk_bf16_f32 v94, v186, v187
	v_cvt_pk_bf16_f32 v95, v184, v185
	v_cvt_pk_bf16_f32 v96, v190, v191
	v_cvt_pk_bf16_f32 v97, v188, v189
	global_store_dwordx4 v[172:173], v[74:77], off
	global_store_dwordx4 v[172:173], v[78:81], off offset:256
	global_store_dwordx4 v[174:175], v[82:85], off
	global_store_dwordx4 v[174:175], v[86:89], off offset:256
	global_store_dwordx4 v[176:177], v[90:93], off
	global_store_dwordx4 v[176:177], v[94:97], off offset:256
	v_pk_add_f32 v[72:73], v[72:73], v[136:137]
	v_pk_add_f32 v[70:71], v[70:71], v[134:135]
	v_pk_add_f32 v[74:75], v[68:69], v[132:133]
	v_pk_add_f32 v[68:69], v[66:67], v[130:131]
	v_cvt_pk_bf16_f32 v66, v70, v71
	v_cvt_pk_bf16_f32 v67, v72, v73
	v_cvt_pk_bf16_f32 v68, v68, v69
	v_cvt_pk_bf16_f32 v69, v74, v75
	global_store_dwordx4 v[178:179], v[66:69], off offset:256
	v_pk_add_f32 v[64:65], v[64:65], v[144:145]
	v_pk_add_f32 v[62:63], v[62:63], v[142:143]
	v_add_u32_e32 v66, 0x80, v169
	v_mad_i64_i32 v[66:67], s[22:23], v66, s42, v[162:163]
	v_pk_add_f32 v[68:69], v[60:61], v[140:141]
	v_pk_add_f32 v[60:61], v[58:59], v[138:139]
	v_lshl_add_u64 v[66:67], v[66:67], 0, v[170:171]
	v_cvt_pk_bf16_f32 v58, v62, v63
	v_cvt_pk_bf16_f32 v59, v64, v65
	v_cvt_pk_bf16_f32 v60, v60, v61
	v_cvt_pk_bf16_f32 v61, v68, v69
	global_store_dwordx4 v[66:67], v[58:61], off
	v_pk_add_f32 v[52:53], v[52:53], v[136:137]
	v_pk_add_f32 v[50:51], v[50:51], v[134:135]
	v_pk_add_f32 v[58:59], v[44:45], v[132:133]
	v_pk_add_f32 v[44:45], v[42:43], v[130:131]
	v_cvt_pk_bf16_f32 v42, v50, v51
	v_cvt_pk_bf16_f32 v43, v52, v53
	v_cvt_pk_bf16_f32 v44, v44, v45
	v_cvt_pk_bf16_f32 v45, v58, v59
	global_store_dwordx4 v[66:67], v[42:45], off offset:256
	v_pk_add_f32 v[48:49], v[48:49], v[140:141]
	v_pk_add_f32 v[46:47], v[46:47], v[138:139]
	v_add_u32_e32 v42, 0x90, v169
	v_mad_i64_i32 v[42:43], s[22:23], v42, s42, v[162:163]
	v_lshl_add_u64 v[50:51], v[42:43], 0, v[170:171]
	v_pk_add_f32 v[44:45], v[56:57], v[144:145]
	v_pk_add_f32 v[42:43], v[54:55], v[142:143]
	v_pk_add_f32 v[36:37], v[36:37], v[136:137]
	v_cvt_pk_bf16_f32 v42, v42, v43
	v_cvt_pk_bf16_f32 v43, v44, v45
	v_cvt_pk_bf16_f32 v44, v46, v47
	v_cvt_pk_bf16_f32 v45, v48, v49
	global_store_dwordx4 v[50:51], v[42:45], off
	v_pk_add_f32 v[34:35], v[34:35], v[134:135]
	v_pk_add_f32 v[32:33], v[32:33], v[140:141]
	v_pk_add_f32 v[42:43], v[28:29], v[132:133]
	v_pk_add_f32 v[28:29], v[26:27], v[130:131]
	v_cvt_pk_bf16_f32 v26, v34, v35
	v_cvt_pk_bf16_f32 v27, v36, v37
	v_cvt_pk_bf16_f32 v28, v28, v29
	v_cvt_pk_bf16_f32 v29, v42, v43
	global_store_dwordx4 v[50:51], v[26:29], off offset:256
	v_pk_add_f32 v[30:31], v[30:31], v[138:139]
	v_pk_add_f32 v[20:21], v[20:21], v[136:137]
	v_add_u32_e32 v26, 0xa0, v169
	v_mad_i64_i32 v[26:27], s[22:23], v26, s42, v[162:163]
	v_lshl_add_u64 v[34:35], v[26:27], 0, v[170:171]
	v_pk_add_f32 v[28:29], v[40:41], v[144:145]
	v_pk_add_f32 v[26:27], v[38:39], v[142:143]
	v_pk_add_f32 v[18:19], v[18:19], v[134:135]
	v_cvt_pk_bf16_f32 v26, v26, v27
	v_cvt_pk_bf16_f32 v27, v28, v29
	v_cvt_pk_bf16_f32 v28, v30, v31
	v_cvt_pk_bf16_f32 v29, v32, v33
	global_store_dwordx4 v[34:35], v[26:29], off
	v_pk_add_f32 v[16:17], v[16:17], v[140:141]
	v_pk_add_f32 v[14:15], v[14:15], v[138:139]
	v_pk_add_f32 v[26:27], v[12:13], v[132:133]
	v_pk_add_f32 v[12:13], v[10:11], v[130:131]
	v_cvt_pk_bf16_f32 v10, v18, v19
	v_cvt_pk_bf16_f32 v11, v20, v21
	v_cvt_pk_bf16_f32 v12, v12, v13
	v_cvt_pk_bf16_f32 v13, v26, v27
	global_store_dwordx4 v[34:35], v[10:13], off offset:256
	v_pk_add_f32 v[8:9], v[8:9], v[136:137]
	v_pk_add_f32 v[6:7], v[6:7], v[134:135]
	v_add_u32_e32 v10, 0xb0, v169
	v_mad_i64_i32 v[10:11], s[22:23], v10, s42, v[162:163]
	v_lshl_add_u64 v[18:19], v[10:11], 0, v[170:171]
	v_pk_add_f32 v[12:13], v[24:25], v[144:145]
	v_pk_add_f32 v[10:11], v[22:23], v[142:143]
	v_cvt_pk_bf16_f32 v98, v194, v195
	v_cvt_pk_bf16_f32 v10, v10, v11
	v_cvt_pk_bf16_f32 v11, v12, v13
	v_cvt_pk_bf16_f32 v12, v14, v15
	v_cvt_pk_bf16_f32 v13, v16, v17
	global_store_dwordx4 v[18:19], v[10:13], off
	v_cvt_pk_bf16_f32 v99, v192, v193
	v_cvt_pk_bf16_f32 v100, v198, v199
	v_pk_add_f32 v[10:11], v[4:5], v[132:133]
	v_pk_add_f32 v[4:5], v[2:3], v[130:131]
	v_cvt_pk_bf16_f32 v101, v196, v197
	v_cvt_pk_bf16_f32 v2, v6, v7
	v_cvt_pk_bf16_f32 v3, v8, v9
	v_cvt_pk_bf16_f32 v4, v4, v5
	v_cvt_pk_bf16_f32 v5, v10, v11
	global_store_dwordx4 v[178:179], v[98:101], off
	global_store_dwordx4 v[18:19], v[2:5], off offset:256
	s_cbranch_vccnz .LBB0_2611
	s_andn2_b64 vcc, exec, s[6:7]
	s_cbranch_vccnz .LBB0_2610
	s_branch .LBB0_2610

;     __device__ __forceinline__ void operator()(const f32x4 (&acc)[2][2][4][2], const Unit& u, int wr, int wc, int fr, int fq) const {
;         const int row0 = u.pm * BM + wr * 64 + fr; const int col0 = u.pn * BM + wc * 32 + 8 * fq;
;         f32x4 bv[2][2];
;         if (BIAS) {
; #pragma unroll
;             for (int bj = 0; bj < 2; ++bj)
; #pragma unroll
;                 for (int n = 0; n < 2; ++n) bv[bj][n] = *(const f32x4*)(bias + col0 + bj * HALF + 4 * n); }
; #pragma unroll
;         for (int ai = 0; ai < 2; ++ai)
; #pragma unroll
;             for (int m = 0; m < 4; ++m) { bf16_t* rowp = O + (size_t)(row0 + ai * HALF + m * 16) * ldc + col0;
.LBB0_3375:
	v_lshl_or_b32 v168, s54, 8, v163
	v_ashrrev_i32_e32 v169, 31, v168
	v_lshl_add_u64 v[130:131], v[168:169], 2, s[2:3]
	global_load_dwordx4 v[142:145], v[130:131], off
	global_load_dwordx4 v[138:141], v[130:131], off offset:16
	global_load_dwordx4 v[134:137], v[130:131], off offset:512
	s_nop 0
	global_load_dwordx4 v[130:133], v[130:131], off offset:528
	v_lshl_add_u32 v170, s28, 8, v1
	v_or_b32_e32 v172, 16, v170
	v_or_b32_e32 v174, 32, v170
	v_or_b32_e32 v176, 48, v170
	v_ashrrev_i32_e32 v171, 31, v170
	v_ashrrev_i32_e32 v173, 31, v172
	v_ashrrev_i32_e32 v175, 31, v174
	v_ashrrev_i32_e32 v177, 31, v176
	v_readlane_b32 s30, v254, 4
	v_lshlrev_b64 v[170:171], 12, v[170:171]
	v_readlane_b32 s31, v254, 5
	v_lshlrev_b64 v[172:173], 12, v[172:173]
	v_lshlrev_b64 v[174:175], 12, v[174:175]
	v_lshlrev_b64 v[176:177], 12, v[176:177]
	v_lshlrev_b64 v[168:169], 1, v[168:169]
	v_lshl_add_u64 v[170:171], s[30:31], 0, v[170:171]
	v_lshl_add_u64 v[172:173], s[30:31], 0, v[172:173]
	v_lshl_add_u64 v[174:175], s[30:31], 0, v[174:175]
	v_lshl_add_u64 v[176:177], s[30:31], 0, v[176:177]
	v_lshl_add_u64 v[170:171], v[170:171], 0, v[168:169]
	v_lshl_add_u64 v[172:173], v[172:173], 0, v[168:169]
	v_lshl_add_u64 v[174:175], v[174:175], 0, v[168:169]
	v_lshl_add_u64 v[168:169], v[176:177], 0, v[168:169]
	s_waitcnt vmcnt(0)
; __device__ __forceinline__ unsigned cvt_pk_bf16(float lo, float hi) { const bf16x2_cv v = __builtin_convertvector((f32x2_cv){lo, hi}, bf16x2_cv); return __builtin_bit_cast(unsigned, v); }
; #define PG8_BAR __builtin_amdgcn_s_barrier()
;     __device__ __forceinline__ void operator()(const f32x4 (&acc)[2][2][4][2], const Unit& u, int wr, int wc, int fr, int fq) const {
;     ...
;             for (int m = 0; m < 4; ++m) { bf16_t* rowp = O + (size_t)(row0 + ai * HALF + m * 16) * ldc + col0;
; #pragma unroll
;                 for (int bj = 0; bj < 2; ++bj) { f32x4 v0 = acc[ai][bj][m][0], v1 = acc[ai][bj][m][1]; if (BIAS) { v0 = v0 + bv[bj][0]; v1 = v1 + bv[bj][1]; }
;                     u32x4 w; w.x = cvt_pk_bf16(v0[0], v0[1]); w.y = cvt_pk_bf16(v0[2], v0[3]); w.z = cvt_pk_bf16(v1[0], v1[1]); w.w = cvt_pk_bf16(v1[2], v1[3]);
;                     *(u32x4*)(rowp + bj * HALF) = w; } }
; template <class Epi, class Sched, bool ALIGN_EPI = false, bool SP2 = false>
; __device__ __forceinline__ void gemm_phase(PG8_LAS unsigned char* lds, const Gemm g, const Sched& S, const Epi& E) {
;     ...
;         cur = nxt; cA = nA; cB = nB; ++ui;
;         if constexpr (ALIGN_EPI) { if (wr == 1) PG8_BAR; }
	v_pk_add_f32 v[128:129], v[128:129], v[144:145]
	v_pk_add_f32 v[126:127], v[126:127], v[142:143]
	v_pk_add_f32 v[124:125], v[124:125], v[140:141]
	v_pk_add_f32 v[122:123], v[122:123], v[138:139]
	v_pk_add_f32 v[108:109], v[108:109], v[136:137]
	v_pk_add_f32 v[106:107], v[106:107], v[134:135]
	v_pk_add_f32 v[100:101], v[100:101], v[132:133]
	v_pk_add_f32 v[98:99], v[98:99], v[130:131]
	v_pk_add_f32 v[120:121], v[120:121], v[144:145]
	v_pk_add_f32 v[118:119], v[118:119], v[142:143]
	v_pk_add_f32 v[116:117], v[116:117], v[140:141]
	v_pk_add_f32 v[114:115], v[114:115], v[138:139]
	v_pk_add_f32 v[92:93], v[92:93], v[136:137]
	v_pk_add_f32 v[90:91], v[90:91], v[134:135]
	v_pk_add_f32 v[176:177], v[84:85], v[132:133]
	v_pk_add_f32 v[178:179], v[82:83], v[130:131]
	v_pk_add_f32 v[112:113], v[112:113], v[144:145]
	v_pk_add_f32 v[110:111], v[110:111], v[142:143]
	v_pk_add_f32 v[104:105], v[104:105], v[140:141]
	v_pk_add_f32 v[102:103], v[102:103], v[138:139]
	v_pk_add_f32 v[180:181], v[80:81], v[136:137]
	v_pk_add_f32 v[182:183], v[78:79], v[134:135]
	v_pk_add_f32 v[184:185], v[76:77], v[132:133]
	v_pk_add_f32 v[186:187], v[74:75], v[130:131]
	v_pk_add_f32 v[188:189], v[96:97], v[144:145]
	v_pk_add_f32 v[190:191], v[94:95], v[142:143]
	v_pk_add_f32 v[192:193], v[88:89], v[140:141]
	v_pk_add_f32 v[194:195], v[86:87], v[138:139]
	v_cvt_pk_bf16_f32 v74, v126, v127
	v_cvt_pk_bf16_f32 v75, v128, v129
	v_cvt_pk_bf16_f32 v76, v122, v123
	v_cvt_pk_bf16_f32 v77, v124, v125
	v_cvt_pk_bf16_f32 v78, v106, v107
	v_cvt_pk_bf16_f32 v79, v108, v109
	v_cvt_pk_bf16_f32 v80, v98, v99
	v_cvt_pk_bf16_f32 v81, v100, v101
	v_cvt_pk_bf16_f32 v82, v118, v119
	v_cvt_pk_bf16_f32 v83, v120, v121
	v_cvt_pk_bf16_f32 v84, v114, v115
	v_cvt_pk_bf16_f32 v85, v116, v117
	v_cvt_pk_bf16_f32 v86, v90, v91
	v_cvt_pk_bf16_f32 v87, v92, v93
	v_cvt_pk_bf16_f32 v88, v178, v179
	v_cvt_pk_bf16_f32 v89, v176, v177
	v_cvt_pk_bf16_f32 v90, v110, v111
	v_cvt_pk_bf16_f32 v91, v112, v113
	v_cvt_pk_bf16_f32 v92, v102, v103
	v_cvt_pk_bf16_f32 v93, v104, v105
	v_cvt_pk_bf16_f32 v94, v182, v183
	v_cvt_pk_bf16_f32 v95, v180, v181
	v_cvt_pk_bf16_f32 v96, v186, v187
	v_cvt_pk_bf16_f32 v97, v184, v185
	global_store_dwordx4 v[170:171], v[74:77], off
	global_store_dwordx4 v[170:171], v[78:81], off offset:256
	global_store_dwordx4 v[172:173], v[82:85], off
	global_store_dwordx4 v[172:173], v[86:89], off offset:256
	global_store_dwordx4 v[174:175], v[90:93], off
	global_store_dwordx4 v[174:175], v[94:97], off offset:256
	v_cvt_pk_bf16_f32 v74, v190, v191
	v_cvt_pk_bf16_f32 v75, v188, v189
	v_cvt_pk_bf16_f32 v76, v194, v195
	v_cvt_pk_bf16_f32 v77, v192, v193
	global_store_dwordx4 v[168:169], v[74:77], off
	v_pk_add_f32 v[72:73], v[72:73], v[136:137]
	v_pk_add_f32 v[70:71], v[70:71], v[134:135]
	v_pk_add_f32 v[74:75], v[68:69], v[132:133]
	v_pk_add_f32 v[68:69], v[66:67], v[130:131]
	v_cvt_pk_bf16_f32 v66, v70, v71
	v_cvt_pk_bf16_f32 v67, v72, v73
	v_cvt_pk_bf16_f32 v68, v68, v69
	v_cvt_pk_bf16_f32 v69, v74, v75
	v_pk_add_f32 v[62:63], v[62:63], v[142:143]
	global_store_dwordx4 v[168:169], v[66:69], off offset:256
	v_pk_add_f32 v[64:65], v[64:65], v[144:145]
	v_pk_add_f32 v[52:53], v[52:53], v[136:137]
	v_pk_add_f32 v[68:69], v[60:61], v[140:141]
	v_pk_add_f32 v[60:61], v[58:59], v[138:139]
	v_cvt_pk_bf16_f32 v58, v62, v63
	v_add_co_u32_e32 v62, vcc, s50, v170
	v_cvt_pk_bf16_f32 v59, v64, v65
	v_cvt_pk_bf16_f32 v60, v60, v61
	v_cvt_pk_bf16_f32 v61, v68, v69
	v_addc_co_u32_e32 v63, vcc, 0, v171, vcc
	global_store_dwordx4 v[62:63], v[58:61], off
	v_pk_add_f32 v[50:51], v[50:51], v[134:135]
	v_lshl_add_u64 v[66:67], v[170:171], 0, s[6:7]
	v_pk_add_f32 v[58:59], v[44:45], v[132:133]
	v_pk_add_f32 v[44:45], v[42:43], v[130:131]
	v_cvt_pk_bf16_f32 v42, v50, v51
	v_cvt_pk_bf16_f32 v43, v52, v53
	v_cvt_pk_bf16_f32 v44, v44, v45
	v_cvt_pk_bf16_f32 v45, v58, v59
	global_store_dwordx4 v[66:67], v[42:45], off offset:256
	v_pk_add_f32 v[46:47], v[46:47], v[138:139]
	v_pk_add_f32 v[48:49], v[48:49], v[140:141]
	v_pk_add_f32 v[44:45], v[56:57], v[144:145]
	v_pk_add_f32 v[42:43], v[54:55], v[142:143]
	v_pk_add_f32 v[36:37], v[36:37], v[136:137]
	v_cvt_pk_bf16_f32 v42, v42, v43
	v_cvt_pk_bf16_f32 v43, v44, v45
	v_cvt_pk_bf16_f32 v44, v46, v47
	v_add_co_u32_e32 v46, vcc, s51, v170
	v_cvt_pk_bf16_f32 v45, v48, v49
	s_nop 0
	v_addc_co_u32_e32 v47, vcc, 0, v171, vcc
	global_store_dwordx4 v[46:47], v[42:45], off
	v_pk_add_f32 v[34:35], v[34:35], v[134:135]
	v_lshl_add_u64 v[50:51], v[170:171], 0, s[14:15]
	v_pk_add_f32 v[42:43], v[28:29], v[132:133]
	v_pk_add_f32 v[28:29], v[26:27], v[130:131]
	v_cvt_pk_bf16_f32 v26, v34, v35
	v_cvt_pk_bf16_f32 v27, v36, v37
	v_cvt_pk_bf16_f32 v28, v28, v29
	v_cvt_pk_bf16_f32 v29, v42, v43
	global_store_dwordx4 v[50:51], v[26:29], off offset:256
	v_pk_add_f32 v[30:31], v[30:31], v[138:139]
	v_pk_add_f32 v[32:33], v[32:33], v[140:141]
	v_pk_add_f32 v[28:29], v[40:41], v[144:145]
	v_pk_add_f32 v[26:27], v[38:39], v[142:143]
	v_pk_add_f32 v[20:21], v[20:21], v[136:137]
	v_cvt_pk_bf16_f32 v26, v26, v27
	v_cvt_pk_bf16_f32 v27, v28, v29
	v_cvt_pk_bf16_f32 v28, v30, v31
	v_add_co_u32_e32 v30, vcc, s52, v170
	v_cvt_pk_bf16_f32 v29, v32, v33
	s_nop 0
	v_addc_co_u32_e32 v31, vcc, 0, v171, vcc
	global_store_dwordx4 v[30:31], v[26:29], off
	v_pk_add_f32 v[18:19], v[18:19], v[134:135]
	v_lshl_add_u64 v[34:35], v[170:171], 0, s[16:17]
	v_pk_add_f32 v[26:27], v[12:13], v[132:133]
	v_pk_add_f32 v[12:13], v[10:11], v[130:131]
	v_cvt_pk_bf16_f32 v10, v18, v19
	v_cvt_pk_bf16_f32 v11, v20, v21
	v_cvt_pk_bf16_f32 v12, v12, v13
	v_cvt_pk_bf16_f32 v13, v26, v27
	global_store_dwordx4 v[34:35], v[10:13], off offset:256
	v_pk_add_f32 v[14:15], v[14:15], v[138:139]
	v_pk_add_f32 v[16:17], v[16:17], v[140:141]
	v_pk_add_f32 v[12:13], v[24:25], v[144:145]
	v_pk_add_f32 v[10:11], v[22:23], v[142:143]
	v_pk_add_f32 v[8:9], v[8:9], v[136:137]
	v_cvt_pk_bf16_f32 v10, v10, v11
	v_cvt_pk_bf16_f32 v11, v12, v13
	v_cvt_pk_bf16_f32 v12, v14, v15
	v_add_co_u32_e32 v14, vcc, s53, v170
	v_cvt_pk_bf16_f32 v13, v16, v17
	s_nop 0
	v_addc_co_u32_e32 v15, vcc, 0, v171, vcc
	global_store_dwordx4 v[14:15], v[10:13], off
	v_pk_add_f32 v[6:7], v[6:7], v[134:135]
	v_lshl_add_u64 v[18:19], v[170:171], 0, s[18:19]
	v_pk_add_f32 v[10:11], v[4:5], v[132:133]
	v_pk_add_f32 v[4:5], v[2:3], v[130:131]
	v_cvt_pk_bf16_f32 v2, v6, v7
	v_cvt_pk_bf16_f32 v3, v8, v9
	v_cvt_pk_bf16_f32 v4, v4, v5
	v_cvt_pk_bf16_f32 v5, v10, v11
	s_andn2_b64 vcc, exec, s[4:5]
	s_mov_b64 s[4:5], -1
	global_store_dwordx4 v[18:19], v[2:5], off offset:256
	s_cbranch_vccnz .LBB0_3368
	s_andn2_b64 vcc, exec, s[8:9]
	s_cbranch_vccnz .LBB0_3367
	s_branch .LBB0_3367

; __device__ __forceinline__ unsigned cvt_pk_bf16(float lo, float hi) { const bf16x2_cv v = __builtin_convertvector((f32x2_cv){lo, hi}, bf16x2_cv); return __builtin_bit_cast(unsigned, v); }
; __device__ __forceinline__ float sigmoid_f(float x) { return __builtin_amdgcn_rcpf(1.0f + __expf(-x)); }
;     __device__ __forceinline__ void operator()(const f32x4 (&acc)[2][2][4][2], const Unit& u, int wr, int wc, int fr, int fq) const {
;         const int row0 = u.pm * BM + wr * 64 + fr; const int col0 = u.pn * HALF + wc * 32 + 8 * fq;
; #pragma unroll
;         for (int ai = 0; ai < 2; ++ai)
; #pragma unroll
;             for (int m = 0; m < 4; ++m) { bf16_t* rowp = O + (size_t)(row0 + ai * HALF + m * 16) * ldc + col0;
;                 float o[8];
; #pragma unroll
;                 for (int n = 0; n < 2; ++n)
; #pragma unroll
;                     for (int j = 0; j < 4; ++j) { const float g = acc[ai][0][m][n][j], up = acc[ai][1][m][n][j]; o[n * 4 + j] = g * sigmoid_f(g) * up; }
;                 u32x4 w; w.x = cvt_pk_bf16(o[0], o[1]); w.y = cvt_pk_bf16(o[2], o[3]); w.z = cvt_pk_bf16(o[4], o[5]); w.w = cvt_pk_bf16(o[6], o[7]);
;                 *(u32x4*)rowp = w; }
.LBB0_3503:
	v_mul_f32_e32 v146, 0xbfb8aa3b, v126
	v_exp_f32_e32 v146, v146
	v_mul_f32_e32 v147, 0xbfb8aa3b, v127
	v_exp_f32_e32 v147, v147
	v_lshl_or_b32 v154, s43, 7, v149
	v_add_f32_e32 v146, 1.0, v146
	v_rcp_f32_e32 v156, v146
	v_add_f32_e32 v146, 1.0, v147
	v_rcp_f32_e32 v157, v146
	v_lshl_add_u32 v153, s18, 8, v1
	v_ashrrev_i32_e32 v155, 31, v154
	v_mov_b64_e32 v[146:147], s[84:85]
	v_pk_mul_f32 v[126:127], v[126:127], v[156:157]
	v_mul_f32_e32 v156, 0xbfb8aa3b, v128
	v_mul_f32_e32 v157, 0xbfb8aa3b, v129
	v_exp_f32_e32 v156, v156
	v_exp_f32_e32 v157, v157
	v_pk_mul_f32 v[118:119], v[126:127], v[118:119]
	v_mad_i64_i32 v[158:159], s[20:21], v153, s42, v[146:147]
	v_add_f32_e32 v126, 1.0, v156
	v_add_f32_e32 v127, 1.0, v157
	v_mul_f32_e32 v156, 0xbfb8aa3b, v122
	v_mul_f32_e32 v157, 0xbfb8aa3b, v123
	v_rcp_f32_e32 v126, v126
	v_rcp_f32_e32 v127, v127
	v_exp_f32_e32 v156, v156
	v_exp_f32_e32 v157, v157
	s_andn2_b64 vcc, exec, s[4:5]
	v_pk_mul_f32 v[126:127], v[128:129], v[126:127]
	v_add_f32_e32 v128, 1.0, v156
	v_add_f32_e32 v129, 1.0, v157
	v_mul_f32_e32 v156, 0xbfb8aa3b, v124
	v_mul_f32_e32 v157, 0xbfb8aa3b, v125
	v_exp_f32_e32 v156, v156
	v_exp_f32_e32 v157, v157
	v_rcp_f32_e32 v128, v128
	v_rcp_f32_e32 v129, v129
	v_add_f32_e32 v156, 1.0, v156
	v_add_f32_e32 v157, 1.0, v157
	v_rcp_f32_e32 v156, v156
	v_rcp_f32_e32 v157, v157
	v_pk_mul_f32 v[122:123], v[122:123], v[128:129]
	v_pk_mul_f32 v[120:121], v[126:127], v[120:121]
	v_pk_mul_f32 v[122:123], v[122:123], v[114:115]
	v_pk_mul_f32 v[114:115], v[124:125], v[156:157]
	s_mov_b64 s[4:5], -1
	v_pk_mul_f32 v[124:125], v[114:115], v[116:117]
	v_cvt_pk_bf16_f32 v117, v120, v121
	v_mul_f32_e32 v120, 0xbfb8aa3b, v110
	v_mul_f32_e32 v121, 0xbfb8aa3b, v111
	v_exp_f32_e32 v120, v120
	v_exp_f32_e32 v121, v121
	v_lshlrev_b64 v[114:115], 1, v[154:155]
	v_lshl_add_u64 v[126:127], v[158:159], 0, v[114:115]
	v_cvt_pk_bf16_f32 v116, v118, v119
	v_cvt_pk_bf16_f32 v118, v122, v123
	v_cvt_pk_bf16_f32 v119, v124, v125
	global_store_dwordx4 v[126:127], v[116:119], off
	s_nop 1
	v_add_f32_e32 v116, 1.0, v120
	v_add_f32_e32 v117, 1.0, v121
	v_rcp_f32_e32 v116, v116
	v_rcp_f32_e32 v117, v117
	v_or_b32_e32 v118, 16, v153
	v_mad_i64_i32 v[118:119], s[20:21], v118, s42, v[146:147]
	v_pk_mul_f32 v[110:111], v[110:111], v[116:117]
	v_mul_f32_e32 v116, 0xbfb8aa3b, v112
	v_mul_f32_e32 v117, 0xbfb8aa3b, v113
	v_exp_f32_e32 v116, v116
	v_exp_f32_e32 v117, v117
	v_pk_mul_f32 v[102:103], v[110:111], v[102:103]
	v_add_f32_e32 v110, 1.0, v116
	v_add_f32_e32 v111, 1.0, v117
	v_mul_f32_e32 v116, 0xbfb8aa3b, v106
	v_mul_f32_e32 v117, 0xbfb8aa3b, v107
	v_rcp_f32_e32 v110, v110
	v_rcp_f32_e32 v111, v111
	v_exp_f32_e32 v116, v116
	v_exp_f32_e32 v117, v117
	v_pk_mul_f32 v[110:111], v[112:113], v[110:111]
	v_add_f32_e32 v112, 1.0, v116
	v_add_f32_e32 v113, 1.0, v117
	v_mul_f32_e32 v116, 0xbfb8aa3b, v108
	v_mul_f32_e32 v117, 0xbfb8aa3b, v109
	v_exp_f32_e32 v116, v116
	v_exp_f32_e32 v117, v117
	v_rcp_f32_e32 v112, v112
	v_rcp_f32_e32 v113, v113
	v_add_f32_e32 v116, 1.0, v116
	v_add_f32_e32 v117, 1.0, v117
	v_rcp_f32_e32 v116, v116
	v_rcp_f32_e32 v117, v117
	v_pk_mul_f32 v[106:107], v[106:107], v[112:113]
	v_pk_mul_f32 v[104:105], v[110:111], v[104:105]
	v_pk_mul_f32 v[106:107], v[106:107], v[98:99]
	v_pk_mul_f32 v[98:99], v[108:109], v[116:117]
	v_lshl_add_u64 v[110:111], v[118:119], 0, v[114:115]
	v_pk_mul_f32 v[108:109], v[98:99], v[100:101]
	v_cvt_pk_bf16_f32 v98, v102, v103
	v_mul_f32_e32 v102, 0xbfb8aa3b, v94
	v_mul_f32_e32 v103, 0xbfb8aa3b, v95
	v_exp_f32_e32 v102, v102
	v_exp_f32_e32 v103, v103
	v_cvt_pk_bf16_f32 v99, v104, v105
	v_cvt_pk_bf16_f32 v100, v106, v107
	v_cvt_pk_bf16_f32 v101, v108, v109
	global_store_dwordx4 v[110:111], v[98:101], off
	s_nop 1
	v_add_f32_e32 v98, 1.0, v102
	v_add_f32_e32 v99, 1.0, v103
	v_rcp_f32_e32 v98, v98
	v_rcp_f32_e32 v99, v99
	v_or_b32_e32 v100, 32, v153
	v_mad_i64_i32 v[100:101], s[20:21], v100, s42, v[146:147]
	v_pk_mul_f32 v[94:95], v[94:95], v[98:99]
	v_mul_f32_e32 v98, 0xbfb8aa3b, v96
	v_mul_f32_e32 v99, 0xbfb8aa3b, v97
	v_exp_f32_e32 v98, v98
	v_exp_f32_e32 v99, v99
	v_pk_mul_f32 v[86:87], v[94:95], v[86:87]
	v_add_f32_e32 v94, 1.0, v98
	v_add_f32_e32 v95, 1.0, v99
	v_mul_f32_e32 v98, 0xbfb8aa3b, v90
	v_mul_f32_e32 v99, 0xbfb8aa3b, v91
	v_rcp_f32_e32 v94, v94
	v_rcp_f32_e32 v95, v95
	v_exp_f32_e32 v98, v98
	v_exp_f32_e32 v99, v99
	v_pk_mul_f32 v[94:95], v[96:97], v[94:95]
	v_add_f32_e32 v96, 1.0, v98
	v_add_f32_e32 v97, 1.0, v99
	v_mul_f32_e32 v98, 0xbfb8aa3b, v92
	v_mul_f32_e32 v99, 0xbfb8aa3b, v93
	v_exp_f32_e32 v98, v98
	v_exp_f32_e32 v99, v99
	v_rcp_f32_e32 v96, v96
	v_rcp_f32_e32 v97, v97
	v_add_f32_e32 v98, 1.0, v98
	v_add_f32_e32 v99, 1.0, v99
	v_rcp_f32_e32 v98, v98
	v_rcp_f32_e32 v99, v99
	v_pk_mul_f32 v[90:91], v[90:91], v[96:97]
	v_pk_mul_f32 v[88:89], v[94:95], v[88:89]
	v_pk_mul_f32 v[90:91], v[90:91], v[82:83]
	v_pk_mul_f32 v[82:83], v[92:93], v[98:99]
	v_lshl_add_u64 v[94:95], v[100:101], 0, v[114:115]
	v_pk_mul_f32 v[92:93], v[82:83], v[84:85]
	v_cvt_pk_bf16_f32 v82, v86, v87
	v_mul_f32_e32 v86, 0xbfb8aa3b, v78
	v_mul_f32_e32 v87, 0xbfb8aa3b, v79
	v_exp_f32_e32 v86, v86
	v_exp_f32_e32 v87, v87
	v_cvt_pk_bf16_f32 v83, v88, v89
	v_cvt_pk_bf16_f32 v84, v90, v91
	v_cvt_pk_bf16_f32 v85, v92, v93
	global_store_dwordx4 v[94:95], v[82:85], off
	s_nop 1
	v_add_f32_e32 v82, 1.0, v86
	v_add_f32_e32 v83, 1.0, v87
	v_rcp_f32_e32 v82, v82
	v_rcp_f32_e32 v83, v83
	v_or_b32_e32 v84, 48, v153
	v_mad_i64_i32 v[84:85], s[20:21], v84, s42, v[146:147]
	v_pk_mul_f32 v[78:79], v[78:79], v[82:83]
	v_mul_f32_e32 v82, 0xbfb8aa3b, v80
	v_mul_f32_e32 v83, 0xbfb8aa3b, v81
	v_exp_f32_e32 v82, v82
; __device__ __forceinline__ unsigned cvt_pk_bf16(float lo, float hi) { const bf16x2_cv v = __builtin_convertvector((f32x2_cv){lo, hi}, bf16x2_cv); return __builtin_bit_cast(unsigned, v); }
; __device__ __forceinline__ float sigmoid_f(float x) { return __builtin_amdgcn_rcpf(1.0f + __expf(-x)); }
;     __device__ __forceinline__ void operator()(const f32x4 (&acc)[2][2][4][2], const Unit& u, int wr, int wc, int fr, int fq) const {
;     ...
;             for (int m = 0; m < 4; ++m) { bf16_t* rowp = O + (size_t)(row0 + ai * HALF + m * 16) * ldc + col0;
;                 float o[8];
; #pragma unroll
;                 for (int n = 0; n < 2; ++n)
; #pragma unroll
;                     for (int j = 0; j < 4; ++j) { const float g = acc[ai][0][m][n][j], up = acc[ai][1][m][n][j]; o[n * 4 + j] = g * sigmoid_f(g) * up; }
;                 u32x4 w; w.x = cvt_pk_bf16(o[0], o[1]); w.y = cvt_pk_bf16(o[2], o[3]); w.z = cvt_pk_bf16(o[4], o[5]); w.w = cvt_pk_bf16(o[6], o[7]);
;                 *(u32x4*)rowp = w; }
	v_exp_f32_e32 v83, v83
	v_pk_mul_f32 v[70:71], v[78:79], v[70:71]
	v_add_f32_e32 v78, 1.0, v82
	v_add_f32_e32 v79, 1.0, v83
	v_mul_f32_e32 v82, 0xbfb8aa3b, v74
	v_mul_f32_e32 v83, 0xbfb8aa3b, v75
	v_rcp_f32_e32 v78, v78
	v_rcp_f32_e32 v79, v79
	v_exp_f32_e32 v82, v82
	v_exp_f32_e32 v83, v83
	v_pk_mul_f32 v[78:79], v[80:81], v[78:79]
	v_add_f32_e32 v80, 1.0, v82
	v_add_f32_e32 v81, 1.0, v83
	v_mul_f32_e32 v82, 0xbfb8aa3b, v76
	v_mul_f32_e32 v83, 0xbfb8aa3b, v77
	v_exp_f32_e32 v82, v82
	v_exp_f32_e32 v83, v83
	v_rcp_f32_e32 v80, v80
	v_rcp_f32_e32 v81, v81
	v_add_f32_e32 v82, 1.0, v82
	v_add_f32_e32 v83, 1.0, v83
	v_rcp_f32_e32 v82, v82
	v_rcp_f32_e32 v83, v83
	v_pk_mul_f32 v[74:75], v[74:75], v[80:81]
	v_pk_mul_f32 v[72:73], v[78:79], v[72:73]
	v_pk_mul_f32 v[74:75], v[74:75], v[66:67]
	v_pk_mul_f32 v[66:67], v[76:77], v[82:83]
	v_lshl_add_u64 v[78:79], v[84:85], 0, v[114:115]
	v_pk_mul_f32 v[76:77], v[66:67], v[68:69]
	v_cvt_pk_bf16_f32 v66, v70, v71
	v_mul_f32_e32 v70, 0xbfb8aa3b, v62
	v_mul_f32_e32 v71, 0xbfb8aa3b, v63
	v_exp_f32_e32 v70, v70
	v_exp_f32_e32 v71, v71
	v_cvt_pk_bf16_f32 v67, v72, v73
	v_cvt_pk_bf16_f32 v68, v74, v75
	v_cvt_pk_bf16_f32 v69, v76, v77
	global_store_dwordx4 v[78:79], v[66:69], off
	s_nop 1
	v_add_f32_e32 v66, 1.0, v70
	v_add_f32_e32 v67, 1.0, v71
	v_rcp_f32_e32 v66, v66
	v_rcp_f32_e32 v67, v67
	v_add_u32_e32 v68, 0x80, v153
	v_mad_i64_i32 v[68:69], s[20:21], v68, s42, v[146:147]
	v_pk_mul_f32 v[62:63], v[62:63], v[66:67]
	v_mul_f32_e32 v66, 0xbfb8aa3b, v64
	v_mul_f32_e32 v67, 0xbfb8aa3b, v65
	v_exp_f32_e32 v66, v66
	v_exp_f32_e32 v67, v67
	v_pk_mul_f32 v[54:55], v[62:63], v[54:55]
	v_add_f32_e32 v62, 1.0, v66
	v_add_f32_e32 v63, 1.0, v67
	v_mul_f32_e32 v66, 0xbfb8aa3b, v58
	v_mul_f32_e32 v67, 0xbfb8aa3b, v59
	v_rcp_f32_e32 v62, v62
	v_rcp_f32_e32 v63, v63
	v_exp_f32_e32 v66, v66
	v_exp_f32_e32 v67, v67
	v_pk_mul_f32 v[62:63], v[64:65], v[62:63]
	v_add_f32_e32 v64, 1.0, v66
	v_add_f32_e32 v65, 1.0, v67
	v_mul_f32_e32 v66, 0xbfb8aa3b, v60
	v_mul_f32_e32 v67, 0xbfb8aa3b, v61
	v_exp_f32_e32 v66, v66
	v_exp_f32_e32 v67, v67
	v_rcp_f32_e32 v64, v64
	v_rcp_f32_e32 v65, v65
	v_add_f32_e32 v66, 1.0, v66
	v_add_f32_e32 v67, 1.0, v67
	v_rcp_f32_e32 v66, v66
	v_rcp_f32_e32 v67, v67
	v_pk_mul_f32 v[58:59], v[58:59], v[64:65]
	v_pk_mul_f32 v[56:57], v[62:63], v[56:57]
	v_pk_mul_f32 v[58:59], v[58:59], v[50:51]
	v_pk_mul_f32 v[50:51], v[60:61], v[66:67]
	v_lshl_add_u64 v[62:63], v[68:69], 0, v[114:115]
	v_pk_mul_f32 v[60:61], v[50:51], v[52:53]
	v_cvt_pk_bf16_f32 v50, v54, v55
	v_mul_f32_e32 v54, 0xbfb8aa3b, v46
	v_mul_f32_e32 v55, 0xbfb8aa3b, v47
	v_exp_f32_e32 v54, v54
	v_exp_f32_e32 v55, v55
	v_cvt_pk_bf16_f32 v51, v56, v57
	v_cvt_pk_bf16_f32 v52, v58, v59
	v_cvt_pk_bf16_f32 v53, v60, v61
	global_store_dwordx4 v[62:63], v[50:53], off
	s_nop 1
	v_add_f32_e32 v50, 1.0, v54
	v_add_f32_e32 v51, 1.0, v55
	v_rcp_f32_e32 v50, v50
	v_rcp_f32_e32 v51, v51
	v_add_u32_e32 v52, 0x90, v153
	v_mad_i64_i32 v[52:53], s[20:21], v52, s42, v[146:147]
	v_pk_mul_f32 v[46:47], v[46:47], v[50:51]
	v_mul_f32_e32 v50, 0xbfb8aa3b, v48
	v_mul_f32_e32 v51, 0xbfb8aa3b, v49
	v_exp_f32_e32 v50, v50
	v_exp_f32_e32 v51, v51
	v_pk_mul_f32 v[38:39], v[46:47], v[38:39]
	v_add_f32_e32 v46, 1.0, v50
	v_add_f32_e32 v47, 1.0, v51
	v_mul_f32_e32 v50, 0xbfb8aa3b, v42
	v_mul_f32_e32 v51, 0xbfb8aa3b, v43
	v_rcp_f32_e32 v46, v46
	v_rcp_f32_e32 v47, v47
	v_exp_f32_e32 v50, v50
	v_exp_f32_e32 v51, v51
	v_pk_mul_f32 v[46:47], v[48:49], v[46:47]
	v_add_f32_e32 v48, 1.0, v50
	v_add_f32_e32 v49, 1.0, v51
	v_mul_f32_e32 v50, 0xbfb8aa3b, v44
	v_mul_f32_e32 v51, 0xbfb8aa3b, v45
	v_exp_f32_e32 v50, v50
	v_exp_f32_e32 v51, v51
	v_rcp_f32_e32 v48, v48
	v_rcp_f32_e32 v49, v49
	v_add_f32_e32 v50, 1.0, v50
; __device__ __forceinline__ unsigned cvt_pk_bf16(float lo, float hi) { const bf16x2_cv v = __builtin_convertvector((f32x2_cv){lo, hi}, bf16x2_cv); return __builtin_bit_cast(unsigned, v); }
; __device__ __forceinline__ float sigmoid_f(float x) { return __builtin_amdgcn_rcpf(1.0f + __expf(-x)); }
; #define PG8_BAR __builtin_amdgcn_s_barrier()
;     __device__ __forceinline__ void operator()(const f32x4 (&acc)[2][2][4][2], const Unit& u, int wr, int wc, int fr, int fq) const {
;     ...
;             for (int m = 0; m < 4; ++m) { bf16_t* rowp = O + (size_t)(row0 + ai * HALF + m * 16) * ldc + col0;
;                 float o[8];
; #pragma unroll
;                 for (int n = 0; n < 2; ++n)
; #pragma unroll
;                     for (int j = 0; j < 4; ++j) { const float g = acc[ai][0][m][n][j], up = acc[ai][1][m][n][j]; o[n * 4 + j] = g * sigmoid_f(g) * up; }
;                 u32x4 w; w.x = cvt_pk_bf16(o[0], o[1]); w.y = cvt_pk_bf16(o[2], o[3]); w.z = cvt_pk_bf16(o[4], o[5]); w.w = cvt_pk_bf16(o[6], o[7]);
;                 *(u32x4*)rowp = w; }
; template <class Epi, class Sched, bool ALIGN_EPI = false, bool SP2 = false>
; __device__ __forceinline__ void gemm_phase(PG8_LAS unsigned char* lds, const Gemm g, const Sched& S, const Epi& E) {
;     ...
;         cur = nxt; cA = nA; cB = nB; ++ui;
;         if constexpr (ALIGN_EPI) { if (wr == 1) PG8_BAR; }
	v_add_f32_e32 v51, 1.0, v51
	v_rcp_f32_e32 v50, v50
	v_rcp_f32_e32 v51, v51
	v_pk_mul_f32 v[42:43], v[42:43], v[48:49]
	v_pk_mul_f32 v[40:41], v[46:47], v[40:41]
	v_pk_mul_f32 v[42:43], v[42:43], v[34:35]
	v_pk_mul_f32 v[34:35], v[44:45], v[50:51]
	v_lshl_add_u64 v[46:47], v[52:53], 0, v[114:115]
	v_pk_mul_f32 v[44:45], v[34:35], v[36:37]
	v_cvt_pk_bf16_f32 v34, v38, v39
	v_mul_f32_e32 v38, 0xbfb8aa3b, v30
	v_mul_f32_e32 v39, 0xbfb8aa3b, v31
	v_exp_f32_e32 v38, v38
	v_exp_f32_e32 v39, v39
	v_cvt_pk_bf16_f32 v35, v40, v41
	v_cvt_pk_bf16_f32 v36, v42, v43
	v_cvt_pk_bf16_f32 v37, v44, v45
	global_store_dwordx4 v[46:47], v[34:37], off
	s_nop 1
	v_add_f32_e32 v34, 1.0, v38
	v_add_f32_e32 v35, 1.0, v39
	v_rcp_f32_e32 v34, v34
	v_rcp_f32_e32 v35, v35
	v_add_u32_e32 v36, 0xa0, v153
	v_mad_i64_i32 v[36:37], s[20:21], v36, s42, v[146:147]
	v_pk_mul_f32 v[30:31], v[30:31], v[34:35]
	v_mul_f32_e32 v34, 0xbfb8aa3b, v32
	v_mul_f32_e32 v35, 0xbfb8aa3b, v33
	v_exp_f32_e32 v34, v34
	v_exp_f32_e32 v35, v35
	v_pk_mul_f32 v[22:23], v[30:31], v[22:23]
	v_add_f32_e32 v30, 1.0, v34
	v_add_f32_e32 v31, 1.0, v35
	v_mul_f32_e32 v34, 0xbfb8aa3b, v26
	v_mul_f32_e32 v35, 0xbfb8aa3b, v27
	v_rcp_f32_e32 v30, v30
	v_rcp_f32_e32 v31, v31
	v_exp_f32_e32 v34, v34
	v_exp_f32_e32 v35, v35
	v_pk_mul_f32 v[30:31], v[32:33], v[30:31]
	v_add_f32_e32 v32, 1.0, v34
	v_add_f32_e32 v33, 1.0, v35
	v_mul_f32_e32 v34, 0xbfb8aa3b, v28
	v_mul_f32_e32 v35, 0xbfb8aa3b, v29
	v_exp_f32_e32 v34, v34
	v_exp_f32_e32 v35, v35
	v_rcp_f32_e32 v32, v32
	v_rcp_f32_e32 v33, v33
	v_add_f32_e32 v34, 1.0, v34
	v_add_f32_e32 v35, 1.0, v35
	v_rcp_f32_e32 v34, v34
	v_rcp_f32_e32 v35, v35
	v_pk_mul_f32 v[26:27], v[26:27], v[32:33]
	v_pk_mul_f32 v[24:25], v[30:31], v[24:25]
	v_pk_mul_f32 v[26:27], v[26:27], v[18:19]
	v_pk_mul_f32 v[18:19], v[28:29], v[34:35]
	v_lshl_add_u64 v[30:31], v[36:37], 0, v[114:115]
	v_pk_mul_f32 v[28:29], v[18:19], v[20:21]
	v_cvt_pk_bf16_f32 v18, v22, v23
	v_mul_f32_e32 v22, 0xbfb8aa3b, v14
	v_mul_f32_e32 v23, 0xbfb8aa3b, v15
	v_exp_f32_e32 v22, v22
	v_exp_f32_e32 v23, v23
	v_cvt_pk_bf16_f32 v19, v24, v25
	v_cvt_pk_bf16_f32 v20, v26, v27
	v_cvt_pk_bf16_f32 v21, v28, v29
	global_store_dwordx4 v[30:31], v[18:21], off
	s_nop 1
	v_add_f32_e32 v18, 1.0, v22
	v_add_f32_e32 v19, 1.0, v23
	v_rcp_f32_e32 v18, v18
	v_rcp_f32_e32 v19, v19
	v_add_u32_e32 v20, 0xb0, v153
	v_mad_i64_i32 v[20:21], s[20:21], v20, s42, v[146:147]
	v_pk_mul_f32 v[14:15], v[14:15], v[18:19]
	v_mul_f32_e32 v18, 0xbfb8aa3b, v16
	v_mul_f32_e32 v19, 0xbfb8aa3b, v17
	v_exp_f32_e32 v18, v18
	v_exp_f32_e32 v19, v19
	v_pk_mul_f32 v[6:7], v[14:15], v[6:7]
	v_add_f32_e32 v14, 1.0, v18
	v_add_f32_e32 v15, 1.0, v19
	v_mul_f32_e32 v18, 0xbfb8aa3b, v10
	v_mul_f32_e32 v19, 0xbfb8aa3b, v11
	v_rcp_f32_e32 v14, v14
	v_rcp_f32_e32 v15, v15
	v_exp_f32_e32 v18, v18
	v_exp_f32_e32 v19, v19
	v_pk_mul_f32 v[14:15], v[16:17], v[14:15]
	v_add_f32_e32 v16, 1.0, v18
	v_add_f32_e32 v17, 1.0, v19
	v_mul_f32_e32 v18, 0xbfb8aa3b, v12
	v_mul_f32_e32 v19, 0xbfb8aa3b, v13
	v_exp_f32_e32 v18, v18
	v_exp_f32_e32 v19, v19
	v_rcp_f32_e32 v16, v16
	v_rcp_f32_e32 v17, v17
	v_add_f32_e32 v18, 1.0, v18
	v_add_f32_e32 v19, 1.0, v19
	v_rcp_f32_e32 v18, v18
	v_rcp_f32_e32 v19, v19
	v_pk_mul_f32 v[10:11], v[10:11], v[16:17]
	v_pk_mul_f32 v[8:9], v[14:15], v[8:9]
	v_pk_mul_f32 v[10:11], v[10:11], v[2:3]
	v_pk_mul_f32 v[2:3], v[12:13], v[18:19]
	v_lshl_add_u64 v[14:15], v[20:21], 0, v[114:115]
	v_pk_mul_f32 v[12:13], v[2:3], v[4:5]
	v_cvt_pk_bf16_f32 v2, v6, v7
	v_cvt_pk_bf16_f32 v3, v8, v9
	v_cvt_pk_bf16_f32 v4, v10, v11
	v_cvt_pk_bf16_f32 v5, v12, v13
	global_store_dwordx4 v[14:15], v[2:5], off
	s_cbranch_vccnz .LBB0_3496
	s_andn2_b64 vcc, exec, s[2:3]
	s_cbranch_vccnz .LBB0_3495
	s_branch .LBB0_3495
